# FFN-up epilogue: conv weights staged per wave in an LDS slot by one LDS-DMA load at tile start (static LDS 8 KB), read back with ds_read_b128 instead of 16 replicated global loads per lane
# speedup vs baseline: 1.0572x; 1.0035x over previous
; #define PG8_STAGE(bufoff, gbase, voff) do { _Pragma("unroll") for (int _i = 0; _i < 2; ++_i) \
;         __builtin_amdgcn_global_load_lds((const unsigned*)((const char*)(gbase) + (voff)[_i]), (LAS unsigned*)(lds + (bufoff) + ldsw + _i * 8192), 16, 0, 0); } while (0)
; #define PG8_LDA(dst, b, h) do { _Pragma("unroll") for (int m = 0; m < 4; ++m) _Pragma("unroll") for (int k = 0; k < 2; ++k) dst[m][k] = *(const LAS bf16x8*)(lds + PG8_SA(b, h) + aoff + m * 2048 + k * 1024); } while (0)
; #define PG8_LDB(dst, b, h) do { _Pragma("unroll") for (int n = 0; n < 2; ++n) _Pragma("unroll") for (int k = 0; k < 2; ++k) dst[n][k] = *(const LAS bf16x8*)(lds + PG8_SB(b, h) + boff + n * 2048 + k * 1024); } while (0)
; #define PG8_WAIT_V(n) asm volatile("s_waitcnt vmcnt(" #n ")" ::: "memory")
; #define PG8_WAIT_L(n) asm volatile("s_waitcnt lgkmcnt(" #n ")" ::: "memory")
; #define PG8_BAR __builtin_amdgcn_s_barrier()
; #define PG8_SCHED __builtin_amdgcn_sched_barrier(0)
; template <class Epi, class S_t>
; __device__ __forceinline__ void gemm_phase(LAS unsigned char* lds, int lda, int ldb, const S_t& S, const Epi& E) {
;     ...
;             PG8_LDB(B0, 0, 0); PG8_SCHED; PG8_LDA(At, 0, 0); PG8_STAGE(PG8_SA(1, 1), a1 + hstepA, voffA);
;             PG8_WAIT_L(8); PG8_BAR; PG8_WAIT_L(0); PG8_MMA(0, 0, At, B0); PG8_BAR; PG8_SCHED;
;             PG8_LDB(B1, 0, 1); PG8_STAGE(PG8_SB(0, 0), b2, voffB);
;             PG8_BAR; PG8_WAIT_L(0); PG8_MMA(0, 1, At, B1); PG8_BAR;
;             PG8_LDA(At, 0, 1); PG8_STAGE(PG8_SA(0, 0), a2, voffA);
;             PG8_BAR; PG8_WAIT_L(0); PG8_MMA(1, 0, At, B0); PG8_BAR; PG8_SCHED;
;             PG8_STAGE(PG8_SB(0, 1), b2 + hstepB, voffB);
;             PG8_WAIT_V(6); PG8_BAR; PG8_MMA(1, 1, At, B1); PG8_BAR;
;     __device__ __forceinline__ void operator()(const f32x4 (&acc)[2][2][4][2], const Unit& u, int wr, int wc, int fr, int fq) const {
;     ...
;             const int jc = j0 + 4 * n;
;             const f32x4 wg0 = *(const f32x4*)(wconv + jc), wg1 = *(const f32x4*)(wconv + 2 * DFF + jc), wg2 = *(const f32x4*)(wconv + 4 * DFF + jc), bg = *(const f32x4*)(bconv + jc);
;             const f32x4 wv0 = *(const f32x4*)(wconv + DFF + jc), wv1 = *(const f32x4*)(wconv + 3 * DFF + jc), wv2 = *(const f32x4*)(wconv + 5 * DFF + jc), bv = *(const f32x4*)(bconv + DFF + jc);
.LBB0_1199:
	v_readlane_b32 s100, v254, 41
	v_readlane_b32 s101, v254, 42
	v_readlane_b32 s98, v254, 43
	v_readlane_b32 s99, v254, 44
	v_and_b32_e32 v128, 63, v212
	v_lshrrev_b32_e32 v129, 3, v128
	v_and_b32_e32 v128, 7, v128
	v_and_b32_e32 v130, 0x60, v219
	v_lshl_or_b32 v130, s42, 7, v130
	v_lshlrev_b32_e32 v130, 2, v130
	v_lshl_add_u32 v130, v128, 4, v130
	v_cmp_gt_u32_e32 vcc, 6, v129
	v_subrev_u32_e32 v131, 6, v129
	v_mov_b32_e32 v132, s100
	v_mov_b32_e32 v133, s98
	v_mov_b32_e32 v134, s101
	v_mov_b32_e32 v135, s99
	v_cndmask_b32_e32 v131, v131, v129, vcc
	v_cndmask_b32_e32 v132, v133, v132, vcc
	v_cndmask_b32_e32 v134, v135, v134, vcc
	v_mul_u32_u24_e32 v131, 0x6000, v131
	v_add_u32_e32 v130, v130, v131
	v_add_co_u32_e32 v130, vcc, v132, v130
	v_addc_co_u32_e32 v131, vcc, 0, v134, vcc
	v_readfirstlane_b32 s98, v212
	s_lshr_b32 s98, s98, 6
	s_lshl_b32 s98, s98, 10
	s_add_i32 m0, s98, 0x20840
	s_nop 0
	global_load_lds_dwordx4 v[130:131], off
	s_add_u32 s74, s74, 0x80080
	s_addc_u32 s75, s75, 0
	s_add_u32 s0, s76, 0x100
	s_addc_u32 s1, s77, 0
	s_mov_b32 s5, -2
	v_mov_b64_e32 v[0:1], 0
	v_mov_b64_e32 v[2:3], 0
	v_mov_b64_e32 v[4:5], 0
	v_mov_b64_e32 v[6:7], 0
	v_mov_b64_e32 v[8:9], 0
	v_mov_b64_e32 v[10:11], 0
	v_mov_b64_e32 v[12:13], 0
	v_mov_b64_e32 v[14:15], 0
	v_mov_b64_e32 v[16:17], 0
	v_mov_b64_e32 v[18:19], 0
	v_mov_b64_e32 v[20:21], 0
	v_mov_b64_e32 v[22:23], 0
	v_mov_b64_e32 v[24:25], 0
	v_mov_b64_e32 v[26:27], 0
	v_mov_b64_e32 v[28:29], 0
	v_mov_b64_e32 v[30:31], 0
	v_mov_b64_e32 v[32:33], 0
	v_mov_b64_e32 v[34:35], 0
	v_mov_b64_e32 v[36:37], 0
	v_mov_b64_e32 v[38:39], 0
	v_mov_b64_e32 v[40:41], 0
	v_mov_b64_e32 v[42:43], 0
	v_mov_b64_e32 v[44:45], 0
	v_mov_b64_e32 v[46:47], 0
	v_mov_b64_e32 v[48:49], 0
	v_mov_b64_e32 v[50:51], 0
	v_mov_b64_e32 v[52:53], 0
	v_mov_b64_e32 v[54:55], 0
	v_mov_b64_e32 v[56:57], 0
	v_mov_b64_e32 v[58:59], 0
	v_mov_b64_e32 v[60:61], 0
	v_mov_b64_e32 v[62:63], 0
	v_mov_b64_e32 v[64:65], 0
	v_mov_b64_e32 v[66:67], 0
	v_mov_b64_e32 v[68:69], 0
	v_mov_b64_e32 v[70:71], 0
	v_mov_b64_e32 v[72:73], 0
	v_mov_b64_e32 v[74:75], 0
	v_mov_b64_e32 v[76:77], 0
	v_mov_b64_e32 v[78:79], 0
	v_mov_b64_e32 v[80:81], 0
	v_mov_b64_e32 v[82:83], 0
	v_mov_b64_e32 v[84:85], 0
	v_mov_b64_e32 v[86:87], 0
	v_mov_b64_e32 v[88:89], 0
	v_mov_b64_e32 v[90:91], 0
	v_mov_b64_e32 v[92:93], 0
	v_mov_b64_e32 v[94:95], 0
	v_mov_b64_e32 v[96:97], 0
	v_mov_b64_e32 v[98:99], 0
	v_mov_b64_e32 v[100:101], 0
	v_mov_b64_e32 v[102:103], 0
	v_mov_b64_e32 v[104:105], 0
	v_mov_b64_e32 v[106:107], 0
	v_mov_b64_e32 v[108:109], 0
	v_mov_b64_e32 v[110:111], 0
	v_mov_b64_e32 v[112:113], 0
	v_mov_b64_e32 v[114:115], 0
	v_mov_b64_e32 v[116:117], 0
	v_mov_b64_e32 v[118:119], 0
	v_mov_b64_e32 v[120:121], 0
	v_mov_b64_e32 v[122:123], 0
	v_mov_b64_e32 v[124:125], 0
	v_mov_b64_e32 v[126:127], 0
.LBB0_1200:
	ds_read_b128 v[128:131], v223
	ds_read_b128 v[132:135], v223 offset:1024
	ds_read_b128 v[136:139], v223 offset:2048
	ds_read_b128 v[140:143], v223 offset:3072
	s_add_u32 s33, s74, 0xfff80080
	s_addc_u32 s43, s75, -1
	s_cmp_eq_u32 s5, 28
	s_cselect_b32 s79, s69, s43
	s_cselect_b32 s78, s68, s33
	s_cselect_b32 s77, s71, s1
	s_cselect_b32 s76, s70, s0
	s_add_i32 m0, s7, 0xc000
	ds_read_b128 v[144:147], v246
	ds_read_b128 v[148:151], v246 offset:1024
	ds_read_b128 v[152:155], v246 offset:2048
	ds_read_b128 v[156:159], v246 offset:3072
	ds_read_b128 v[160:163], v246 offset:4096
	ds_read_b128 v[164:167], v246 offset:5120
	ds_read_b128 v[168:171], v246 offset:6144
	ds_read_b128 v[172:175], v246 offset:7168
	global_load_lds_dwordx4 v236, s[74:75]
	s_add_i32 m0, s7, 0xe000
	s_nop 0
	global_load_lds_dwordx4 v238, s[74:75]
	s_waitcnt lgkmcnt(8)
	s_barrier
	s_waitcnt lgkmcnt(0)
	s_setprio 1
	s_waitcnt lgkmcnt(0)
	v_mfma_f32_16x16x32_bf16 v[124:127], v[128:131], v[144:147], v[124:127]
	v_mfma_f32_16x16x32_bf16 v[120:123], v[136:139], v[144:147], v[120:123]
	v_mfma_f32_16x16x32_bf16 v[116:119], v[128:131], v[152:155], v[116:119]
	v_mfma_f32_16x16x32_bf16 v[108:111], v[136:139], v[152:155], v[108:111]
	v_mfma_f32_16x16x32_bf16 v[100:103], v[128:131], v[160:163], v[100:103]
	v_mfma_f32_16x16x32_bf16 v[92:95], v[136:139], v[160:163], v[92:95]
	v_mfma_f32_16x16x32_bf16 v[84:87], v[128:131], v[168:171], v[84:87]
	v_mfma_f32_16x16x32_bf16 v[76:79], v[136:139], v[168:171], v[76:79]
	v_mfma_f32_16x16x32_bf16 v[124:127], v[132:135], v[148:151], v[124:127]
	v_mfma_f32_16x16x32_bf16 v[120:123], v[140:143], v[148:151], v[120:123]
	v_mfma_f32_16x16x32_bf16 v[116:119], v[132:135], v[156:159], v[116:119]
	v_mfma_f32_16x16x32_bf16 v[108:111], v[140:143], v[156:159], v[108:111]
	v_mfma_f32_16x16x32_bf16 v[100:103], v[132:135], v[164:167], v[100:103]
	v_mfma_f32_16x16x32_bf16 v[92:95], v[140:143], v[164:167], v[92:95]
	v_mfma_f32_16x16x32_bf16 v[84:87], v[132:135], v[172:175], v[84:87]
	v_mfma_f32_16x16x32_bf16 v[76:79], v[140:143], v[172:175], v[76:79]
	s_setprio 0
	s_barrier
	s_add_i32 s33, s88, s64
	s_add_u32 s98, s76, s38
	s_addc_u32 s99, s77, s39
	s_mov_b32 m0, s33
	ds_read_b128 v[176:179], v247
	ds_read_b128 v[180:183], v247 offset:1024
	ds_read_b128 v[184:187], v247 offset:2048
	ds_read_b128 v[188:191], v247 offset:3072
	global_load_lds_dwordx4 v228, s[76:77]
	s_add_i32 m0, s33, 0x2000
	s_nop 0
	global_load_lds_dwordx4 v224, s[76:77]
	s_barrier
; #define PG8_STAGE(bufoff, gbase, voff) do { _Pragma("unroll") for (int _i = 0; _i < 2; ++_i) \
;         __builtin_amdgcn_global_load_lds((const unsigned*)((const char*)(gbase) + (voff)[_i]), (LAS unsigned*)(lds + (bufoff) + ldsw + _i * 8192), 16, 0, 0); } while (0)
; #define PG8_LDA(dst, b, h) do { _Pragma("unroll") for (int m = 0; m < 4; ++m) _Pragma("unroll") for (int k = 0; k < 2; ++k) dst[m][k] = *(const LAS bf16x8*)(lds + PG8_SA(b, h) + aoff + m * 2048 + k * 1024); } while (0)
; #define PG8_LDB(dst, b, h) do { _Pragma("unroll") for (int n = 0; n < 2; ++n) _Pragma("unroll") for (int k = 0; k < 2; ++k) dst[n][k] = *(const LAS bf16x8*)(lds + PG8_SB(b, h) + boff + n * 2048 + k * 1024); } while (0)
; #define PG8_WAIT_V(n) asm volatile("s_waitcnt vmcnt(" #n ")" ::: "memory")
; #define PG8_WAIT_L(n) asm volatile("s_waitcnt lgkmcnt(" #n ")" ::: "memory")
; #define PG8_BAR __builtin_amdgcn_s_barrier()
; #define PG8_SCHED __builtin_amdgcn_sched_barrier(0)
; template <class Epi, class S_t>
; __device__ __forceinline__ void gemm_phase(LAS unsigned char* lds, int lda, int ldb, const S_t& S, const Epi& E) {
;     ...
;             PG8_LDB(B0, 0, 0); PG8_SCHED; PG8_LDA(At, 0, 0); PG8_STAGE(PG8_SA(1, 1), a1 + hstepA, voffA);
;             PG8_WAIT_L(8); PG8_BAR; PG8_WAIT_L(0); PG8_MMA(0, 0, At, B0); PG8_BAR; PG8_SCHED;
;             PG8_LDB(B1, 0, 1); PG8_STAGE(PG8_SB(0, 0), b2, voffB);
;             PG8_BAR; PG8_WAIT_L(0); PG8_MMA(0, 1, At, B1); PG8_BAR;
;             PG8_LDA(At, 0, 1); PG8_STAGE(PG8_SA(0, 0), a2, voffA);
;             PG8_BAR; PG8_WAIT_L(0); PG8_MMA(1, 0, At, B0); PG8_BAR; PG8_SCHED;
;             PG8_STAGE(PG8_SB(0, 1), b2 + hstepB, voffB);
;             PG8_WAIT_V(6); PG8_BAR; PG8_MMA(1, 1, At, B1); PG8_BAR;
;             PG8_LDB(B0, 1, 0); PG8_SCHED; PG8_LDA(At, 1, 0); PG8_STAGE(PG8_SA(0, 1), a2 + hstepA, voffA);
;             PG8_WAIT_L(8); PG8_BAR; PG8_WAIT_L(0); PG8_MMA(0, 0, At, B0); PG8_BAR; PG8_SCHED;
;             PG8_LDB(B1, 1, 1); PG8_STAGE(PG8_SB(1, 0), b3, voffB);
;             PG8_BAR; PG8_WAIT_L(0); PG8_MMA(0, 1, At, B1); PG8_BAR;
;             PG8_LDA(At, 1, 1); PG8_STAGE(PG8_SA(1, 0), a3, voffA);
;             PG8_BAR; PG8_WAIT_L(0); PG8_MMA(1, 0, At, B0); PG8_BAR; PG8_SCHED;
;             PG8_STAGE(PG8_SB(1, 1), b3 + hstepB, voffB);
;             PG8_WAIT_V(6); PG8_BAR; PG8_MMA(1, 1, At, B1); PG8_BAR;
	s_waitcnt lgkmcnt(0)
	s_setprio 1
	s_waitcnt lgkmcnt(0)
	v_mfma_f32_16x16x32_bf16 v[112:115], v[176:179], v[144:147], v[112:115]
	v_mfma_f32_16x16x32_bf16 v[104:107], v[184:187], v[144:147], v[104:107]
	v_mfma_f32_16x16x32_bf16 v[96:99], v[176:179], v[152:155], v[96:99]
	v_mfma_f32_16x16x32_bf16 v[88:91], v[184:187], v[152:155], v[88:91]
	v_mfma_f32_16x16x32_bf16 v[80:83], v[176:179], v[160:163], v[80:83]
	v_mfma_f32_16x16x32_bf16 v[72:75], v[184:187], v[160:163], v[72:75]
	v_mfma_f32_16x16x32_bf16 v[68:71], v[176:179], v[168:171], v[68:71]
	v_mfma_f32_16x16x32_bf16 v[64:67], v[184:187], v[168:171], v[64:67]
	v_mfma_f32_16x16x32_bf16 v[112:115], v[180:183], v[148:151], v[112:115]
	v_mfma_f32_16x16x32_bf16 v[104:107], v[188:191], v[148:151], v[104:107]
	v_mfma_f32_16x16x32_bf16 v[96:99], v[180:183], v[156:159], v[96:99]
	v_mfma_f32_16x16x32_bf16 v[88:91], v[188:191], v[156:159], v[88:91]
	v_mfma_f32_16x16x32_bf16 v[80:83], v[180:183], v[164:167], v[80:83]
	v_mfma_f32_16x16x32_bf16 v[72:75], v[188:191], v[164:167], v[72:75]
	v_mfma_f32_16x16x32_bf16 v[68:71], v[180:183], v[172:175], v[68:71]
	v_mfma_f32_16x16x32_bf16 v[64:67], v[188:191], v[172:175], v[64:67]
	s_setprio 0
	s_mov_b32 m0, s7
	s_add_u32 s100, s78, s38
	s_addc_u32 s101, s79, s39
	s_barrier
	ds_read_b128 v[144:147], v246 offset:16384
	ds_read_b128 v[148:151], v246 offset:17408
	ds_read_b128 v[152:155], v246 offset:18432
	ds_read_b128 v[156:159], v246 offset:19456
	ds_read_b128 v[160:163], v246 offset:20480
	ds_read_b128 v[164:167], v246 offset:21504
	ds_read_b128 v[168:171], v246 offset:22528
	ds_read_b128 v[172:175], v246 offset:23552
	global_load_lds_dwordx4 v230, s[78:79]
	s_mov_b32 m0, s35
	s_nop 0
	global_load_lds_dwordx4 v226, s[78:79]
	s_barrier
	s_waitcnt lgkmcnt(0)
	s_setprio 1
	s_waitcnt lgkmcnt(0)
	v_mfma_f32_16x16x32_bf16 v[60:63], v[128:131], v[144:147], v[60:63]
	v_mfma_f32_16x16x32_bf16 v[56:59], v[136:139], v[144:147], v[56:59]
	v_mfma_f32_16x16x32_bf16 v[52:55], v[128:131], v[152:155], v[52:55]
	v_mfma_f32_16x16x32_bf16 v[44:47], v[136:139], v[152:155], v[44:47]
	v_mfma_f32_16x16x32_bf16 v[36:39], v[128:131], v[160:163], v[36:39]
	v_mfma_f32_16x16x32_bf16 v[28:31], v[136:139], v[160:163], v[28:31]
	v_mfma_f32_16x16x32_bf16 v[20:23], v[128:131], v[168:171], v[20:23]
	v_mfma_f32_16x16x32_bf16 v[12:15], v[136:139], v[168:171], v[12:15]
	v_mfma_f32_16x16x32_bf16 v[60:63], v[132:135], v[148:151], v[60:63]
	v_mfma_f32_16x16x32_bf16 v[56:59], v[140:143], v[148:151], v[56:59]
	v_mfma_f32_16x16x32_bf16 v[52:55], v[132:135], v[156:159], v[52:55]
	v_mfma_f32_16x16x32_bf16 v[44:47], v[140:143], v[156:159], v[44:47]
	v_mfma_f32_16x16x32_bf16 v[36:39], v[132:135], v[164:167], v[36:39]
	v_mfma_f32_16x16x32_bf16 v[28:31], v[140:143], v[164:167], v[28:31]
	v_mfma_f32_16x16x32_bf16 v[20:23], v[132:135], v[172:175], v[20:23]
	v_mfma_f32_16x16x32_bf16 v[12:15], v[140:143], v[172:175], v[12:15]
	s_setprio 0
	s_barrier
	s_add_u32 s52, s76, 0x80000
	s_addc_u32 s53, s77, 0
	s_add_i32 s33, s89, s64
	s_mov_b32 m0, s33
	s_nop 0
	global_load_lds_dwordx4 v228, s[52:53]
	s_add_i32 m0, s33, 0x2000
	s_nop 0
	global_load_lds_dwordx4 v224, s[52:53]
	s_waitcnt vmcnt(6)
	s_barrier
	s_setprio 1
	v_mfma_f32_16x16x32_bf16 v[48:51], v[176:179], v[144:147], v[48:51]
	v_mfma_f32_16x16x32_bf16 v[40:43], v[184:187], v[144:147], v[40:43]
	v_mfma_f32_16x16x32_bf16 v[32:35], v[176:179], v[152:155], v[32:35]
	v_mfma_f32_16x16x32_bf16 v[24:27], v[184:187], v[152:155], v[24:27]
	v_mfma_f32_16x16x32_bf16 v[16:19], v[176:179], v[160:163], v[16:19]
	v_mfma_f32_16x16x32_bf16 v[8:11], v[184:187], v[160:163], v[8:11]
	v_mfma_f32_16x16x32_bf16 v[4:7], v[176:179], v[168:171], v[4:7]
	v_mfma_f32_16x16x32_bf16 v[0:3], v[184:187], v[168:171], v[0:3]
	v_mfma_f32_16x16x32_bf16 v[48:51], v[180:183], v[148:151], v[48:51]
	v_mfma_f32_16x16x32_bf16 v[40:43], v[188:191], v[148:151], v[40:43]
	v_mfma_f32_16x16x32_bf16 v[32:35], v[180:183], v[156:159], v[32:35]
	v_mfma_f32_16x16x32_bf16 v[24:27], v[188:191], v[156:159], v[24:27]
	v_mfma_f32_16x16x32_bf16 v[16:19], v[180:183], v[164:167], v[16:19]
	v_mfma_f32_16x16x32_bf16 v[8:11], v[188:191], v[164:167], v[8:11]
	v_mfma_f32_16x16x32_bf16 v[4:7], v[180:183], v[172:175], v[4:7]
	v_mfma_f32_16x16x32_bf16 v[0:3], v[188:191], v[172:175], v[0:3]
	s_setprio 0
	v_add_u32_e32 v140, s90, v215
	s_barrier
	ds_read_b128 v[128:131], v140
	ds_read_b128 v[132:135], v140 offset:1024
	ds_read_b128 v[136:139], v140 offset:2048
	ds_read_b128 v[140:143], v140 offset:3072
	s_add_u32 s52, s78, 0x80000
	s_addc_u32 s53, s79, 0
	s_mov_b32 m0, s92
	ds_read_b128 v[144:147], v246 offset:32768
	ds_read_b128 v[148:151], v246 offset:33792
	ds_read_b128 v[152:155], v246 offset:34816
	ds_read_b128 v[156:159], v246 offset:35840
	ds_read_b128 v[160:163], v246 offset:36864
	ds_read_b128 v[164:167], v246 offset:37888
	ds_read_b128 v[168:171], v246 offset:38912
	ds_read_b128 v[172:175], v246 offset:39936
	global_load_lds_dwordx4 v230, s[52:53]
	s_mov_b32 m0, s50
	s_nop 0
	global_load_lds_dwordx4 v226, s[52:53]
	s_waitcnt lgkmcnt(8)
	s_barrier
; #define PG8_STAGE(bufoff, gbase, voff) do { _Pragma("unroll") for (int _i = 0; _i < 2; ++_i) \
;         __builtin_amdgcn_global_load_lds((const unsigned*)((const char*)(gbase) + (voff)[_i]), (LAS unsigned*)(lds + (bufoff) + ldsw + _i * 8192), 16, 0, 0); } while (0)
; #define PG8_LDA(dst, b, h) do { _Pragma("unroll") for (int m = 0; m < 4; ++m) _Pragma("unroll") for (int k = 0; k < 2; ++k) dst[m][k] = *(const LAS bf16x8*)(lds + PG8_SA(b, h) + aoff + m * 2048 + k * 1024); } while (0)
; #define PG8_LDB(dst, b, h) do { _Pragma("unroll") for (int n = 0; n < 2; ++n) _Pragma("unroll") for (int k = 0; k < 2; ++k) dst[n][k] = *(const LAS bf16x8*)(lds + PG8_SB(b, h) + boff + n * 2048 + k * 1024); } while (0)
; #define PG8_WAIT_V(n) asm volatile("s_waitcnt vmcnt(" #n ")" ::: "memory")
; #define PG8_WAIT_L(n) asm volatile("s_waitcnt lgkmcnt(" #n ")" ::: "memory")
; #define PG8_BAR __builtin_amdgcn_s_barrier()
; #define PG8_SCHED __builtin_amdgcn_sched_barrier(0)
; template <class Epi, class S_t>
; __device__ __forceinline__ void gemm_phase(LAS unsigned char* lds, int lda, int ldb, const S_t& S, const Epi& E) {
;     ...
;             PG8_LDB(B0, 0, 0); PG8_SCHED; PG8_LDA(At, 0, 0); PG8_STAGE(PG8_SA(1, 1), a1 + hstepA, voffA);
;             PG8_WAIT_L(8); PG8_BAR; PG8_WAIT_L(0); PG8_MMA(0, 0, At, B0); PG8_BAR; PG8_SCHED;
;             PG8_LDB(B1, 0, 1); PG8_STAGE(PG8_SB(0, 0), b2, voffB);
;             PG8_BAR; PG8_WAIT_L(0); PG8_MMA(0, 1, At, B1); PG8_BAR;
;             PG8_LDA(At, 0, 1); PG8_STAGE(PG8_SA(0, 0), a2, voffA);
;             PG8_BAR; PG8_WAIT_L(0); PG8_MMA(1, 0, At, B0); PG8_BAR; PG8_SCHED;
;             PG8_STAGE(PG8_SB(0, 1), b2 + hstepB, voffB);
;             PG8_WAIT_V(6); PG8_BAR; PG8_MMA(1, 1, At, B1); PG8_BAR;
;             PG8_LDB(B0, 1, 0); PG8_SCHED; PG8_LDA(At, 1, 0); PG8_STAGE(PG8_SA(0, 1), a2 + hstepA, voffA);
;             PG8_WAIT_L(8); PG8_BAR; PG8_WAIT_L(0); PG8_MMA(0, 0, At, B0); PG8_BAR; PG8_SCHED;
;             PG8_LDB(B1, 1, 1); PG8_STAGE(PG8_SB(1, 0), b3, voffB);
;             PG8_BAR; PG8_WAIT_L(0); PG8_MMA(0, 1, At, B1); PG8_BAR;
;             PG8_LDA(At, 1, 1); PG8_STAGE(PG8_SA(1, 0), a3, voffA);
;             PG8_BAR; PG8_WAIT_L(0); PG8_MMA(1, 0, At, B0); PG8_BAR; PG8_SCHED;
;             PG8_STAGE(PG8_SB(1, 1), b3 + hstepB, voffB);
;             PG8_WAIT_V(6); PG8_BAR; PG8_MMA(1, 1, At, B1); PG8_BAR;
	s_waitcnt lgkmcnt(0)
	s_setprio 1
	s_waitcnt lgkmcnt(0)
	v_mfma_f32_16x16x32_bf16 v[124:127], v[128:131], v[144:147], v[124:127]
	v_mfma_f32_16x16x32_bf16 v[120:123], v[136:139], v[144:147], v[120:123]
	v_mfma_f32_16x16x32_bf16 v[116:119], v[128:131], v[152:155], v[116:119]
	v_mfma_f32_16x16x32_bf16 v[108:111], v[136:139], v[152:155], v[108:111]
	v_mfma_f32_16x16x32_bf16 v[100:103], v[128:131], v[160:163], v[100:103]
	v_mfma_f32_16x16x32_bf16 v[92:95], v[136:139], v[160:163], v[92:95]
	v_mfma_f32_16x16x32_bf16 v[84:87], v[128:131], v[168:171], v[84:87]
	v_mfma_f32_16x16x32_bf16 v[76:79], v[136:139], v[168:171], v[76:79]
	v_mfma_f32_16x16x32_bf16 v[124:127], v[132:135], v[148:151], v[124:127]
	v_mfma_f32_16x16x32_bf16 v[120:123], v[140:143], v[148:151], v[120:123]
	v_mfma_f32_16x16x32_bf16 v[116:119], v[132:135], v[156:159], v[116:119]
	v_mfma_f32_16x16x32_bf16 v[108:111], v[140:143], v[156:159], v[108:111]
	v_mfma_f32_16x16x32_bf16 v[100:103], v[132:135], v[164:167], v[100:103]
	v_mfma_f32_16x16x32_bf16 v[92:95], v[140:143], v[164:167], v[92:95]
	v_mfma_f32_16x16x32_bf16 v[84:87], v[132:135], v[172:175], v[84:87]
	v_mfma_f32_16x16x32_bf16 v[76:79], v[140:143], v[172:175], v[76:79]
	s_setprio 0
	s_barrier
	s_add_i32 s33, s90, s64
	v_add_u32_e32 v188, s91, v215
	s_mov_b32 m0, s33
	ds_read_b128 v[176:179], v188
	ds_read_b128 v[180:183], v188 offset:1024
	ds_read_b128 v[184:187], v188 offset:2048
	ds_read_b128 v[188:191], v188 offset:3072
	global_load_lds_dwordx4 v228, s[98:99]
	s_add_i32 m0, s33, 0x2000
	s_nop 0
	global_load_lds_dwordx4 v224, s[98:99]
	s_barrier
	s_waitcnt lgkmcnt(0)
	s_setprio 1
	s_waitcnt lgkmcnt(0)
	v_mfma_f32_16x16x32_bf16 v[112:115], v[176:179], v[144:147], v[112:115]
	v_mfma_f32_16x16x32_bf16 v[104:107], v[184:187], v[144:147], v[104:107]
	v_mfma_f32_16x16x32_bf16 v[96:99], v[176:179], v[152:155], v[96:99]
	v_mfma_f32_16x16x32_bf16 v[88:91], v[184:187], v[152:155], v[88:91]
	v_mfma_f32_16x16x32_bf16 v[80:83], v[176:179], v[160:163], v[80:83]
	v_mfma_f32_16x16x32_bf16 v[72:75], v[184:187], v[160:163], v[72:75]
	v_mfma_f32_16x16x32_bf16 v[68:71], v[176:179], v[168:171], v[68:71]
	v_mfma_f32_16x16x32_bf16 v[64:67], v[184:187], v[168:171], v[64:67]
	v_mfma_f32_16x16x32_bf16 v[112:115], v[180:183], v[148:151], v[112:115]
	v_mfma_f32_16x16x32_bf16 v[104:107], v[188:191], v[148:151], v[104:107]
	v_mfma_f32_16x16x32_bf16 v[96:99], v[180:183], v[156:159], v[96:99]
	v_mfma_f32_16x16x32_bf16 v[88:91], v[188:191], v[156:159], v[88:91]
	v_mfma_f32_16x16x32_bf16 v[80:83], v[180:183], v[164:167], v[80:83]
	v_mfma_f32_16x16x32_bf16 v[72:75], v[188:191], v[164:167], v[72:75]
	v_mfma_f32_16x16x32_bf16 v[68:71], v[180:183], v[172:175], v[68:71]
	v_mfma_f32_16x16x32_bf16 v[64:67], v[188:191], v[172:175], v[64:67]
	s_setprio 0
	s_mov_b32 m0, s96
	s_barrier
	ds_read_b128 v[144:147], v246 offset:49152
	ds_read_b128 v[148:151], v246 offset:50176
	ds_read_b128 v[152:155], v246 offset:51200
	ds_read_b128 v[156:159], v246 offset:52224
	ds_read_b128 v[160:163], v246 offset:53248
	ds_read_b128 v[164:167], v246 offset:54272
	ds_read_b128 v[168:171], v246 offset:55296
	ds_read_b128 v[172:175], v246 offset:56320
	global_load_lds_dwordx4 v230, s[100:101]
	s_mov_b32 m0, s97
	s_nop 0
	global_load_lds_dwordx4 v226, s[100:101]
	s_barrier
	s_waitcnt lgkmcnt(0)
	s_setprio 1
	s_waitcnt lgkmcnt(0)
	v_mfma_f32_16x16x32_bf16 v[60:63], v[128:131], v[144:147], v[60:63]
	v_mfma_f32_16x16x32_bf16 v[56:59], v[136:139], v[144:147], v[56:59]
	v_mfma_f32_16x16x32_bf16 v[52:55], v[128:131], v[152:155], v[52:55]
	v_mfma_f32_16x16x32_bf16 v[44:47], v[136:139], v[152:155], v[44:47]
	v_mfma_f32_16x16x32_bf16 v[36:39], v[128:131], v[160:163], v[36:39]
	v_mfma_f32_16x16x32_bf16 v[28:31], v[136:139], v[160:163], v[28:31]
	v_mfma_f32_16x16x32_bf16 v[20:23], v[128:131], v[168:171], v[20:23]
	v_mfma_f32_16x16x32_bf16 v[12:15], v[136:139], v[168:171], v[12:15]
	v_mfma_f32_16x16x32_bf16 v[60:63], v[132:135], v[148:151], v[60:63]
	v_mfma_f32_16x16x32_bf16 v[56:59], v[140:143], v[148:151], v[56:59]
	v_mfma_f32_16x16x32_bf16 v[52:55], v[132:135], v[156:159], v[52:55]
	v_mfma_f32_16x16x32_bf16 v[44:47], v[140:143], v[156:159], v[44:47]
	v_mfma_f32_16x16x32_bf16 v[36:39], v[132:135], v[164:167], v[36:39]
	v_mfma_f32_16x16x32_bf16 v[28:31], v[140:143], v[164:167], v[28:31]
	v_mfma_f32_16x16x32_bf16 v[20:23], v[132:135], v[172:175], v[20:23]
	v_mfma_f32_16x16x32_bf16 v[12:15], v[140:143], v[172:175], v[12:15]
	s_setprio 0
	s_barrier
	s_add_u32 s52, s76, 0x80080
	s_addc_u32 s53, s77, 0
	s_add_i32 s33, s91, s64
	s_mov_b32 m0, s33
	s_nop 0
	global_load_lds_dwordx4 v228, s[52:53]
	s_add_i32 m0, s33, 0x2000
	s_nop 0
	global_load_lds_dwordx4 v224, s[52:53]
	s_waitcnt vmcnt(6)
	s_barrier
	s_setprio 1
	v_mfma_f32_16x16x32_bf16 v[48:51], v[176:179], v[144:147], v[48:51]
	v_mfma_f32_16x16x32_bf16 v[40:43], v[184:187], v[144:147], v[40:43]
	v_mfma_f32_16x16x32_bf16 v[32:35], v[176:179], v[152:155], v[32:35]
	v_mfma_f32_16x16x32_bf16 v[24:27], v[184:187], v[152:155], v[24:27]
	v_mfma_f32_16x16x32_bf16 v[16:19], v[176:179], v[160:163], v[16:19]
	v_mfma_f32_16x16x32_bf16 v[8:11], v[184:187], v[160:163], v[8:11]
	v_mfma_f32_16x16x32_bf16 v[4:7], v[176:179], v[168:171], v[4:7]
	v_mfma_f32_16x16x32_bf16 v[0:3], v[184:187], v[168:171], v[0:3]
	v_mfma_f32_16x16x32_bf16 v[48:51], v[180:183], v[148:151], v[48:51]
	v_mfma_f32_16x16x32_bf16 v[40:43], v[188:191], v[148:151], v[40:43]
	v_mfma_f32_16x16x32_bf16 v[32:35], v[180:183], v[156:159], v[32:35]
	v_mfma_f32_16x16x32_bf16 v[24:27], v[188:191], v[156:159], v[24:27]
	v_mfma_f32_16x16x32_bf16 v[16:19], v[180:183], v[164:167], v[16:19]
	v_mfma_f32_16x16x32_bf16 v[8:11], v[188:191], v[164:167], v[8:11]
	v_mfma_f32_16x16x32_bf16 v[4:7], v[180:183], v[172:175], v[4:7]
	v_mfma_f32_16x16x32_bf16 v[0:3], v[188:191], v[172:175], v[0:3]
	s_setprio 0
	s_add_i32 s5, s5, 2
	s_add_u32 s74, s74, 0x100
	s_addc_u32 s75, s75, 0
	s_add_u32 s0, s0, 0x100
	s_addc_u32 s1, s1, 0
	s_cmp_gt_u32 s5, 29
	s_barrier
;     __device__ __forceinline__ void operator()(const f32x4 (&acc)[2][2][4][2], const Unit& u, int wr, int wc, int fr, int fq) const {
;     ...
;         const int j0 = u.pn * HALF + wc * 32 + 8 * fq;
;         u32x2 res0[8];
; #pragma unroll
;         for (int n = 0; n < 2; ++n) {
;             asm volatile("" ::: "memory");
;             const int jc = j0 + 4 * n;
;             const f32x4 wg0 = *(const f32x4*)(wconv + jc), wg1 = *(const f32x4*)(wconv + 2 * DFF + jc), wg2 = *(const f32x4*)(wconv + 4 * DFF + jc), bg = *(const f32x4*)(bconv + jc);
;             const f32x4 wv0 = *(const f32x4*)(wconv + DFF + jc), wv1 = *(const f32x4*)(wconv + 3 * DFF + jc), wv2 = *(const f32x4*)(wconv + 5 * DFF + jc), bv = *(const f32x4*)(bconv + DFF + jc);
; #pragma unroll
;             for (int ai = 0; ai < 2; ++ai)
; #pragma unroll
;                 for (int m = 0; m < 4; ++m) { const int row = row0 + ai * HALF + m * 16;
;                     const f32x4 g0 = acc[ai][0][m][n], v0 = acc[ai][1][m][n];
;                     f32x4 gp = (f32x4){0.f, 0.f, 0.f, 0.f}, vp = gp;
;                     if (m > 0) { gp = acc[ai][0][m > 0 ? m - 1 : 0][n]; vp = acc[ai][1][m > 0 ? m - 1 : 0][n]; }
;                     f32x4 f;
; #pragma unroll
;                     for (int j = 0; j < 4; ++j) {
;                         const float g1 = dpp_shr1(dpp_ror1(gp[j]), g0[j]), g2 = dpp_shr2(dpp_ror2(gp[j]), g0[j]);
;                         const float v1 = dpp_shr1(dpp_ror1(vp[j]), v0[j]), v2 = dpp_shr2(dpp_ror2(vp[j]), v0[j]);
;                         const float cg_ = bg[j] + g2 * wg0[j] + g1 * wg1[j] + g0[j] * wg2[j];
;                         const float cv_ = bv[j] + v2 * wv0[j] + v1 * wv1[j] + v0[j] * wv2[j];
;                         f[j] = gelu_tanh(cg_) * cv_; }
;                     u32x2 w; w.x = pk2(f[0], f[1]); w.y = pk2(f[2], f[3]);
;                     if (n == 0) res0[ai * 4 + m] = w;
;                     else if (m > 0 || fr >= 2) { u32x4 w4; w4.x = res0[ai * 4 + m].x; w4.y = res0[ai * 4 + m].y; w4.z = w.x; w4.w = w.y; *(u32x4*)(F + (size_t)row * DFF + j0) = w4; }
;                     if (n == 1 && ((m == 0 && fr < 2) || (m == 3 && fr >= 14))) { const int slot = m == 0 ? fr : fr - 12;
;                         const f32x4 ga = acc[ai][0][m][0], va = acc[ai][1][m][0];
;                         bf16_t* bp = UPB + ((size_t)(row >> 6) * 4 + slot) * (2 * DFF) + col0;
	s_cbranch_scc0 .LBB0_1200
	s_lshl_b32 s5, s72, 8
	s_add_i32 s5, s5, s95
	v_or_b32_e32 v248, s5, v232
	s_cmp_lt_i32 s72, 32
	v_lshl_or_b32 v240, s42, 8, v219
	s_cbranch_scc0 .LBB0_1215
	v_lshl_or_b32 v130, s42, 7, v219
	v_readlane_b32 s16, v254, 33
	v_readlane_b32 s17, v254, 34
	v_readlane_b32 s18, v254, 35
	v_readlane_b32 s19, v254, 36
	v_readlane_b32 s20, v254, 37
	v_readlane_b32 s21, v254, 38
	v_readlane_b32 s22, v254, 39
	v_readlane_b32 s23, v254, 40
	v_readlane_b32 s24, v254, 41
	v_readlane_b32 s25, v254, 42
	v_readlane_b32 s26, v254, 43
	v_readlane_b32 s27, v254, 44
	v_readlane_b32 s28, v254, 45
	v_readlane_b32 s29, v254, 46
	v_readlane_b32 s30, v254, 47
	v_readlane_b32 s31, v254, 48
	v_ashrrev_i32_e32 v131, 31, v130
	s_ashr_i32 s72, s5, 6
	v_lshlrev_b64 v[128:129], 2, v[130:131]
	s_lshl_b32 s72, s72, 2
	s_add_i32 s73, s72, 8
	v_readfirstlane_b32 s98, v212
	v_and_b32_e32 v249, 48, v212
	s_lshr_b32 s98, s98, 6
	s_lshl_b32 s98, s98, 10
	s_add_i32 s98, s98, 0x20840
	v_lshl_add_u32 v249, v249, 1, s98
	ds_read_b128 v[146:149], v249 offset:768
	ds_read_b128 v[178:181], v249 offset:784
	ds_read_b128 v[158:161], v249 offset:512
	ds_read_b128 v[190:193], v249 offset:528
	ds_read_b128 v[162:165], v249 offset:896
	ds_read_b128 v[194:197], v249 offset:912
	ds_read_b128 v[174:177], v249 offset:640
	ds_read_b128 v[206:209], v249 offset:656
	ds_read_b128 v[154:157], v249 offset:256
	ds_read_b128 v[186:189], v249 offset:272
	ds_read_b128 v[170:173], v249 offset:384
	ds_read_b128 v[202:205], v249 offset:400
	ds_read_b128 v[150:153], v249 offset:0
	ds_read_b128 v[182:185], v249 offset:16
	ds_read_b128 v[166:169], v249 offset:128
	ds_read_b128 v[198:201], v249 offset:144
	v_lshl_add_u64 v[242:243], v[130:131], 1, s[40:41]
	v_ashrrev_i32_e32 v241, 31, v240
	s_mov_b32 s98, 0xbdd2d3e8
	s_mov_b32 s99, 0xbdd2d3e8
	s_mov_b32 s100, 1.0
	s_mov_b32 s101, 1.0
	v_mov_b32_e32 v244, 0xc0135761
	v_mov_b32_e32 v245, 0xc0135761
	s_and_saveexec_b64 s[42:43], s[10:11]
	v_or_b32_e32 v144, s72, v232
	v_mov_b64_e32 v[128:129], s[80:81]
	v_mad_u64_u32 v[128:129], vcc, v144, s83, v[128:129]
	v_lshl_add_u64 v[128:129], v[240:241], 1, v[128:129]
	v_cvt_pk_bf16_f32 v132, v124, v125
	v_cvt_pk_bf16_f32 v133, v126, v127
	v_cvt_pk_bf16_f32 v134, v120, v121
	v_cvt_pk_bf16_f32 v135, v122, v123
	v_cvt_pk_bf16_f32 v136, v112, v113
	v_cvt_pk_bf16_f32 v137, v114, v115
	v_cvt_pk_bf16_f32 v138, v104, v105
	v_cvt_pk_bf16_f32 v139, v106, v107
	global_store_dwordx4 v[128:129], v[132:135], off
	global_store_dwordx4 v[128:129], v[136:139], off offset:256
	v_or_b32_e32 v144, s73, v232
	v_mov_b64_e32 v[130:131], s[80:81]
	v_mad_u64_u32 v[130:131], vcc, v144, s83, v[130:131]
	v_lshl_add_u64 v[130:131], v[240:241], 1, v[130:131]
	v_cvt_pk_bf16_f32 v140, v60, v61
	v_cvt_pk_bf16_f32 v141, v62, v63
	v_cvt_pk_bf16_f32 v142, v56, v57
	v_cvt_pk_bf16_f32 v143, v58, v59
	v_cvt_pk_bf16_f32 v250, v48, v49
	v_cvt_pk_bf16_f32 v251, v50, v51
	v_cvt_pk_bf16_f32 v252, v40, v41
	v_cvt_pk_bf16_f32 v253, v42, v43
	global_store_dwordx4 v[130:131], v[140:143], off
	global_store_dwordx4 v[130:131], v[250:253], off offset:256
	s_or_b64 exec, exec, s[42:43]
	s_and_saveexec_b64 s[42:43], s[12:13]
	v_add_u32_e32 v144, s72, v234
	v_mov_b64_e32 v[128:129], s[80:81]
	v_mad_u64_u32 v[128:129], vcc, v144, s83, v[128:129]
	v_lshl_add_u64 v[128:129], v[240:241], 1, v[128:129]
	v_cvt_pk_bf16_f32 v132, v84, v85
	v_cvt_pk_bf16_f32 v133, v86, v87
	v_cvt_pk_bf16_f32 v134, v76, v77
	v_cvt_pk_bf16_f32 v135, v78, v79
	v_cvt_pk_bf16_f32 v136, v68, v69
	v_cvt_pk_bf16_f32 v137, v70, v71
	v_cvt_pk_bf16_f32 v138, v64, v65
	v_cvt_pk_bf16_f32 v139, v66, v67
	global_store_dwordx4 v[128:129], v[132:135], off
	global_store_dwordx4 v[128:129], v[136:139], off offset:256
	s_or_b64 exec, exec, s[42:43]
	s_waitcnt lgkmcnt(0)
	s_nop 4
	v_pk_fma_f32 v[132:133], v[124:125], v[158:159], v[146:147]
	v_pk_fma_f32 v[136:137], v[112:113], v[174:175], v[162:163]
	v_pk_fma_f32 v[134:135], v[126:127], v[160:161], v[148:149]
	v_pk_fma_f32 v[138:139], v[114:115], v[176:177], v[164:165]
	v_fmac_f32_dpp v132, v124, v154 row_shr:1 row_mask:0xf bank_mask:0xf
	v_fmac_f32_dpp v133, v125, v155 row_shr:1 row_mask:0xf bank_mask:0xf
	v_fmac_f32_dpp v134, v126, v156 row_shr:1 row_mask:0xf bank_mask:0xf
	v_fmac_f32_dpp v135, v127, v157 row_shr:1 row_mask:0xf bank_mask:0xf
	v_fmac_f32_dpp v136, v112, v170 row_shr:1 row_mask:0xf bank_mask:0xf
	v_fmac_f32_dpp v137, v113, v171 row_shr:1 row_mask:0xf bank_mask:0xf
	v_fmac_f32_dpp v138, v114, v172 row_shr:1 row_mask:0xf bank_mask:0xf
	v_fmac_f32_dpp v139, v115, v173 row_shr:1 row_mask:0xf bank_mask:0xf
	v_fmac_f32_dpp v132, v124, v150 row_shr:2 row_mask:0xf bank_mask:0xf
	v_fmac_f32_dpp v133, v125, v151 row_shr:2 row_mask:0xf bank_mask:0xf
	v_fmac_f32_dpp v134, v126, v152 row_shr:2 row_mask:0xf bank_mask:0xf
	v_fmac_f32_dpp v135, v127, v153 row_shr:2 row_mask:0xf bank_mask:0xf
	v_fmac_f32_dpp v136, v112, v166 row_shr:2 row_mask:0xf bank_mask:0xf
	v_fmac_f32_dpp v137, v113, v167 row_shr:2 row_mask:0xf bank_mask:0xf
	v_fmac_f32_dpp v138, v114, v168 row_shr:2 row_mask:0xf bank_mask:0xf
	v_fmac_f32_dpp v139, v115, v169 row_shr:2 row_mask:0xf bank_mask:0xf
	v_pk_mul_f32 v[140:141], v[132:133], v[132:133]
	v_pk_mul_f32 v[142:143], v[134:135], v[134:135]
	v_pk_fma_f32 v[140:141], v[140:141], s[98:99], v[244:245]
	v_pk_fma_f32 v[142:143], v[142:143], s[98:99], v[244:245]
	v_pk_mul_f32 v[140:141], v[132:133], v[140:141]
	v_pk_mul_f32 v[142:143], v[134:135], v[142:143]
	v_exp_f32_e32 v140, v140
	v_exp_f32_e32 v141, v141
	v_exp_f32_e32 v142, v142
	v_exp_f32_e32 v143, v143
	v_pk_add_f32 v[140:141], v[140:141], s[100:101]
; __device__ __forceinline__ unsigned pk2(float lo, float hi) { unsigned r; asm("v_cvt_pk_bf16_f32 %0, %1, %2" : "=v"(r) : "v"(lo), "v"(hi)); return r; }
; __device__ __forceinline__ float gelu_tanh(float x) { const float y = 1.5957691216f * (x + 0.044715f * x * x * x); return x * __builtin_amdgcn_rcpf(1.0f + __expf(-y)); }
; __device__ __forceinline__ float dpp_shr1(float old, float src) { return __int_as_float(__builtin_amdgcn_update_dpp(__float_as_int(old), __float_as_int(src), 0x111, 0xf, 0xf, false)); }
; __device__ __forceinline__ float dpp_shr2(float old, float src) { return __int_as_float(__builtin_amdgcn_update_dpp(__float_as_int(old), __float_as_int(src), 0x112, 0xf, 0xf, false)); }
; __device__ __forceinline__ float dpp_ror1(float src) { return __int_as_float(__builtin_amdgcn_update_dpp(0, __float_as_int(src), 0x121, 0xf, 0xf, false)); }
;     __device__ __forceinline__ void operator()(const f32x4 (&acc)[2][2][4][2], const Unit& u, int wr, int wc, int fr, int fq) const {
;     ...
; #pragma unroll
;             for (int ai = 0; ai < 2; ++ai)
; #pragma unroll
;                 for (int m = 0; m < 4; ++m) { const int row = row0 + ai * HALF + m * 16;
;                     const f32x4 g0 = acc[ai][0][m][n], v0 = acc[ai][1][m][n];
;                     f32x4 gp = (f32x4){0.f, 0.f, 0.f, 0.f}, vp = gp;
;                     if (m > 0) { gp = acc[ai][0][m > 0 ? m - 1 : 0][n]; vp = acc[ai][1][m > 0 ? m - 1 : 0][n]; }
;                     f32x4 f;
; #pragma unroll
;                     for (int j = 0; j < 4; ++j) {
;                         const float g1 = dpp_shr1(dpp_ror1(gp[j]), g0[j]), g2 = dpp_shr2(dpp_ror2(gp[j]), g0[j]);
;                         const float v1 = dpp_shr1(dpp_ror1(vp[j]), v0[j]), v2 = dpp_shr2(dpp_ror2(vp[j]), v0[j]);
;                         const float cg_ = bg[j] + g2 * wg0[j] + g1 * wg1[j] + g0[j] * wg2[j];
;                         const float cv_ = bv[j] + v2 * wv0[j] + v1 * wv1[j] + v0[j] * wv2[j];
;                         f[j] = gelu_tanh(cg_) * cv_; }
;                     u32x2 w; w.x = pk2(f[0], f[1]); w.y = pk2(f[2], f[3]);
;                     if (n == 0) res0[ai * 4 + m] = w;
;                     else if (m > 0 || fr >= 2) { u32x4 w4; w4.x = res0[ai * 4 + m].x; w4.y = res0[ai * 4 + m].y; w4.z = w.x; w4.w = w.y; *(u32x4*)(F + (size_t)row * DFF + j0) = w4; }
	v_pk_add_f32 v[142:143], v[142:143], s[100:101]
	v_rcp_f32_e32 v140, v140
	v_rcp_f32_e32 v141, v141
	v_rcp_f32_e32 v142, v142
	v_rcp_f32_e32 v143, v143
	v_pk_mul_f32 v[140:141], v[132:133], v[140:141]
	v_pk_mul_f32 v[142:143], v[134:135], v[142:143]
	v_pk_mul_f32 v[140:141], v[140:141], v[136:137]
	v_pk_mul_f32 v[142:143], v[142:143], v[138:139]
	v_cvt_pk_bf16_f32 v128, v140, v141
	v_cvt_pk_bf16_f32 v129, v142, v143
	v_pk_fma_f32 v[132:133], v[120:121], v[190:191], v[178:179]
	v_pk_fma_f32 v[136:137], v[104:105], v[206:207], v[194:195]
	v_pk_fma_f32 v[134:135], v[122:123], v[192:193], v[180:181]
	v_pk_fma_f32 v[138:139], v[106:107], v[208:209], v[196:197]
	v_fmac_f32_dpp v132, v120, v186 row_shr:1 row_mask:0xf bank_mask:0xf
	v_fmac_f32_dpp v133, v121, v187 row_shr:1 row_mask:0xf bank_mask:0xf
	v_fmac_f32_dpp v134, v122, v188 row_shr:1 row_mask:0xf bank_mask:0xf
	v_fmac_f32_dpp v135, v123, v189 row_shr:1 row_mask:0xf bank_mask:0xf
	v_fmac_f32_dpp v136, v104, v202 row_shr:1 row_mask:0xf bank_mask:0xf
	v_fmac_f32_dpp v137, v105, v203 row_shr:1 row_mask:0xf bank_mask:0xf
	v_fmac_f32_dpp v138, v106, v204 row_shr:1 row_mask:0xf bank_mask:0xf
	v_fmac_f32_dpp v139, v107, v205 row_shr:1 row_mask:0xf bank_mask:0xf
	v_fmac_f32_dpp v132, v120, v182 row_shr:2 row_mask:0xf bank_mask:0xf
	v_fmac_f32_dpp v133, v121, v183 row_shr:2 row_mask:0xf bank_mask:0xf
	v_fmac_f32_dpp v134, v122, v184 row_shr:2 row_mask:0xf bank_mask:0xf
	v_fmac_f32_dpp v135, v123, v185 row_shr:2 row_mask:0xf bank_mask:0xf
	v_fmac_f32_dpp v136, v104, v198 row_shr:2 row_mask:0xf bank_mask:0xf
	v_fmac_f32_dpp v137, v105, v199 row_shr:2 row_mask:0xf bank_mask:0xf
	v_fmac_f32_dpp v138, v106, v200 row_shr:2 row_mask:0xf bank_mask:0xf
	v_fmac_f32_dpp v139, v107, v201 row_shr:2 row_mask:0xf bank_mask:0xf
	v_pk_mul_f32 v[140:141], v[132:133], v[132:133]
	v_pk_mul_f32 v[142:143], v[134:135], v[134:135]
	v_pk_fma_f32 v[140:141], v[140:141], s[98:99], v[244:245]
	v_pk_fma_f32 v[142:143], v[142:143], s[98:99], v[244:245]
	v_pk_mul_f32 v[140:141], v[132:133], v[140:141]
	v_pk_mul_f32 v[142:143], v[134:135], v[142:143]
	v_exp_f32_e32 v140, v140
	v_exp_f32_e32 v141, v141
	v_exp_f32_e32 v142, v142
	v_exp_f32_e32 v143, v143
	v_pk_add_f32 v[140:141], v[140:141], s[100:101]
	v_pk_add_f32 v[142:143], v[142:143], s[100:101]
	v_rcp_f32_e32 v140, v140
	v_rcp_f32_e32 v141, v141
	v_rcp_f32_e32 v142, v142
	v_rcp_f32_e32 v143, v143
	v_pk_mul_f32 v[140:141], v[132:133], v[140:141]
	v_pk_mul_f32 v[142:143], v[134:135], v[142:143]
	v_pk_mul_f32 v[140:141], v[140:141], v[136:137]
	v_pk_mul_f32 v[142:143], v[142:143], v[138:139]
	v_cvt_pk_bf16_f32 v130, v140, v141
	v_cvt_pk_bf16_f32 v131, v142, v143
	s_and_saveexec_b64 s[42:43], s[8:9]
	v_mad_u64_u32 v[144:145], vcc, v248, s4, v[242:243]
	global_store_dwordx4 v[144:145], v[128:131], off nt
	s_or_b64 exec, exec, s[42:43]
	s_nop 4
	v_pk_fma_f32 v[132:133], v[116:117], v[158:159], v[146:147]
	v_pk_fma_f32 v[136:137], v[96:97], v[174:175], v[162:163]
	v_pk_fma_f32 v[134:135], v[118:119], v[160:161], v[148:149]
	v_pk_fma_f32 v[138:139], v[98:99], v[176:177], v[164:165]
	v_fmac_f32_dpp v132, v116, v154 row_shr:1 row_mask:0xf bank_mask:0xf
	v_fmac_f32_dpp v133, v117, v155 row_shr:1 row_mask:0xf bank_mask:0xf
	v_fmac_f32_dpp v134, v118, v156 row_shr:1 row_mask:0xf bank_mask:0xf
	v_fmac_f32_dpp v135, v119, v157 row_shr:1 row_mask:0xf bank_mask:0xf
	v_fmac_f32_dpp v136, v96, v170 row_shr:1 row_mask:0xf bank_mask:0xf
	v_fmac_f32_dpp v137, v97, v171 row_shr:1 row_mask:0xf bank_mask:0xf
	v_fmac_f32_dpp v138, v98, v172 row_shr:1 row_mask:0xf bank_mask:0xf
	v_fmac_f32_dpp v139, v99, v173 row_shr:1 row_mask:0xf bank_mask:0xf
	v_fmac_f32_dpp v132, v124, v154 row_shl:15 row_mask:0xf bank_mask:0xf
	v_fmac_f32_dpp v133, v125, v155 row_shl:15 row_mask:0xf bank_mask:0xf
	v_fmac_f32_dpp v134, v126, v156 row_shl:15 row_mask:0xf bank_mask:0xf
	v_fmac_f32_dpp v135, v127, v157 row_shl:15 row_mask:0xf bank_mask:0xf
	v_fmac_f32_dpp v136, v112, v170 row_shl:15 row_mask:0xf bank_mask:0xf
	v_fmac_f32_dpp v137, v113, v171 row_shl:15 row_mask:0xf bank_mask:0xf
	v_fmac_f32_dpp v138, v114, v172 row_shl:15 row_mask:0xf bank_mask:0xf
	v_fmac_f32_dpp v139, v115, v173 row_shl:15 row_mask:0xf bank_mask:0xf
	v_fmac_f32_dpp v132, v116, v150 row_shr:2 row_mask:0xf bank_mask:0xf
	v_fmac_f32_dpp v133, v117, v151 row_shr:2 row_mask:0xf bank_mask:0xf
	v_fmac_f32_dpp v134, v118, v152 row_shr:2 row_mask:0xf bank_mask:0xf
	v_fmac_f32_dpp v135, v119, v153 row_shr:2 row_mask:0xf bank_mask:0xf
	v_fmac_f32_dpp v136, v96, v166 row_shr:2 row_mask:0xf bank_mask:0xf
	v_fmac_f32_dpp v137, v97, v167 row_shr:2 row_mask:0xf bank_mask:0xf
	v_fmac_f32_dpp v138, v98, v168 row_shr:2 row_mask:0xf bank_mask:0xf
	v_fmac_f32_dpp v139, v99, v169 row_shr:2 row_mask:0xf bank_mask:0xf
	v_fmac_f32_dpp v132, v124, v150 row_shl:14 row_mask:0xf bank_mask:0xf
	v_fmac_f32_dpp v133, v125, v151 row_shl:14 row_mask:0xf bank_mask:0xf
	v_fmac_f32_dpp v134, v126, v152 row_shl:14 row_mask:0xf bank_mask:0xf
	v_fmac_f32_dpp v135, v127, v153 row_shl:14 row_mask:0xf bank_mask:0xf
	v_fmac_f32_dpp v136, v112, v166 row_shl:14 row_mask:0xf bank_mask:0xf
	v_fmac_f32_dpp v137, v113, v167 row_shl:14 row_mask:0xf bank_mask:0xf
	v_fmac_f32_dpp v138, v114, v168 row_shl:14 row_mask:0xf bank_mask:0xf
	v_fmac_f32_dpp v139, v115, v169 row_shl:14 row_mask:0xf bank_mask:0xf
	v_pk_mul_f32 v[140:141], v[132:133], v[132:133]
	v_pk_mul_f32 v[142:143], v[134:135], v[134:135]
	v_pk_fma_f32 v[140:141], v[140:141], s[98:99], v[244:245]
	v_pk_fma_f32 v[142:143], v[142:143], s[98:99], v[244:245]
	v_pk_mul_f32 v[140:141], v[132:133], v[140:141]
	v_pk_mul_f32 v[142:143], v[134:135], v[142:143]
; __device__ __forceinline__ unsigned pk2(float lo, float hi) { unsigned r; asm("v_cvt_pk_bf16_f32 %0, %1, %2" : "=v"(r) : "v"(lo), "v"(hi)); return r; }
; __device__ __forceinline__ float gelu_tanh(float x) { const float y = 1.5957691216f * (x + 0.044715f * x * x * x); return x * __builtin_amdgcn_rcpf(1.0f + __expf(-y)); }
; __device__ __forceinline__ float dpp_shr1(float old, float src) { return __int_as_float(__builtin_amdgcn_update_dpp(__float_as_int(old), __float_as_int(src), 0x111, 0xf, 0xf, false)); }
; __device__ __forceinline__ float dpp_shr2(float old, float src) { return __int_as_float(__builtin_amdgcn_update_dpp(__float_as_int(old), __float_as_int(src), 0x112, 0xf, 0xf, false)); }
; __device__ __forceinline__ float dpp_ror1(float src) { return __int_as_float(__builtin_amdgcn_update_dpp(0, __float_as_int(src), 0x121, 0xf, 0xf, false)); }
;     __device__ __forceinline__ void operator()(const f32x4 (&acc)[2][2][4][2], const Unit& u, int wr, int wc, int fr, int fq) const {
;     ...
; #pragma unroll
;             for (int ai = 0; ai < 2; ++ai)
; #pragma unroll
;                 for (int m = 0; m < 4; ++m) { const int row = row0 + ai * HALF + m * 16;
;                     const f32x4 g0 = acc[ai][0][m][n], v0 = acc[ai][1][m][n];
;                     f32x4 gp = (f32x4){0.f, 0.f, 0.f, 0.f}, vp = gp;
;                     if (m > 0) { gp = acc[ai][0][m > 0 ? m - 1 : 0][n]; vp = acc[ai][1][m > 0 ? m - 1 : 0][n]; }
;                     f32x4 f;
; #pragma unroll
;                     for (int j = 0; j < 4; ++j) {
;                         const float g1 = dpp_shr1(dpp_ror1(gp[j]), g0[j]), g2 = dpp_shr2(dpp_ror2(gp[j]), g0[j]);
;                         const float v1 = dpp_shr1(dpp_ror1(vp[j]), v0[j]), v2 = dpp_shr2(dpp_ror2(vp[j]), v0[j]);
;                         const float cg_ = bg[j] + g2 * wg0[j] + g1 * wg1[j] + g0[j] * wg2[j];
;                         const float cv_ = bv[j] + v2 * wv0[j] + v1 * wv1[j] + v0[j] * wv2[j];
;                         f[j] = gelu_tanh(cg_) * cv_; }
;                     u32x2 w; w.x = pk2(f[0], f[1]); w.y = pk2(f[2], f[3]);
;                     if (n == 0) res0[ai * 4 + m] = w;
;                     else if (m > 0 || fr >= 2) { u32x4 w4; w4.x = res0[ai * 4 + m].x; w4.y = res0[ai * 4 + m].y; w4.z = w.x; w4.w = w.y; *(u32x4*)(F + (size_t)row * DFF + j0) = w4; }
	v_exp_f32_e32 v140, v140
	v_exp_f32_e32 v141, v141
	v_exp_f32_e32 v142, v142
	v_exp_f32_e32 v143, v143
	v_pk_add_f32 v[140:141], v[140:141], s[100:101]
	v_pk_add_f32 v[142:143], v[142:143], s[100:101]
	v_rcp_f32_e32 v140, v140
	v_rcp_f32_e32 v141, v141
	v_rcp_f32_e32 v142, v142
	v_rcp_f32_e32 v143, v143
	v_pk_mul_f32 v[140:141], v[132:133], v[140:141]
	v_pk_mul_f32 v[142:143], v[134:135], v[142:143]
	v_pk_mul_f32 v[140:141], v[140:141], v[136:137]
	v_pk_mul_f32 v[142:143], v[142:143], v[138:139]
	v_cvt_pk_bf16_f32 v250, v140, v141
	v_cvt_pk_bf16_f32 v251, v142, v143
	v_pk_fma_f32 v[132:133], v[108:109], v[190:191], v[178:179]
	v_pk_fma_f32 v[136:137], v[88:89], v[206:207], v[194:195]
	v_pk_fma_f32 v[134:135], v[110:111], v[192:193], v[180:181]
	v_pk_fma_f32 v[138:139], v[90:91], v[208:209], v[196:197]
	v_fmac_f32_dpp v132, v108, v186 row_shr:1 row_mask:0xf bank_mask:0xf
	v_fmac_f32_dpp v133, v109, v187 row_shr:1 row_mask:0xf bank_mask:0xf
	v_fmac_f32_dpp v134, v110, v188 row_shr:1 row_mask:0xf bank_mask:0xf
	v_fmac_f32_dpp v135, v111, v189 row_shr:1 row_mask:0xf bank_mask:0xf
	v_fmac_f32_dpp v136, v88, v202 row_shr:1 row_mask:0xf bank_mask:0xf
	v_fmac_f32_dpp v137, v89, v203 row_shr:1 row_mask:0xf bank_mask:0xf
	v_fmac_f32_dpp v138, v90, v204 row_shr:1 row_mask:0xf bank_mask:0xf
	v_fmac_f32_dpp v139, v91, v205 row_shr:1 row_mask:0xf bank_mask:0xf
	v_fmac_f32_dpp v132, v120, v186 row_shl:15 row_mask:0xf bank_mask:0xf
	v_fmac_f32_dpp v133, v121, v187 row_shl:15 row_mask:0xf bank_mask:0xf
	v_fmac_f32_dpp v134, v122, v188 row_shl:15 row_mask:0xf bank_mask:0xf
	v_fmac_f32_dpp v135, v123, v189 row_shl:15 row_mask:0xf bank_mask:0xf
	v_fmac_f32_dpp v136, v104, v202 row_shl:15 row_mask:0xf bank_mask:0xf
	v_fmac_f32_dpp v137, v105, v203 row_shl:15 row_mask:0xf bank_mask:0xf
	v_fmac_f32_dpp v138, v106, v204 row_shl:15 row_mask:0xf bank_mask:0xf
	v_fmac_f32_dpp v139, v107, v205 row_shl:15 row_mask:0xf bank_mask:0xf
	v_fmac_f32_dpp v132, v108, v182 row_shr:2 row_mask:0xf bank_mask:0xf
	v_fmac_f32_dpp v133, v109, v183 row_shr:2 row_mask:0xf bank_mask:0xf
	v_fmac_f32_dpp v134, v110, v184 row_shr:2 row_mask:0xf bank_mask:0xf
	v_fmac_f32_dpp v135, v111, v185 row_shr:2 row_mask:0xf bank_mask:0xf
	v_fmac_f32_dpp v136, v88, v198 row_shr:2 row_mask:0xf bank_mask:0xf
	v_fmac_f32_dpp v137, v89, v199 row_shr:2 row_mask:0xf bank_mask:0xf
	v_fmac_f32_dpp v138, v90, v200 row_shr:2 row_mask:0xf bank_mask:0xf
	v_fmac_f32_dpp v139, v91, v201 row_shr:2 row_mask:0xf bank_mask:0xf
	v_fmac_f32_dpp v132, v120, v182 row_shl:14 row_mask:0xf bank_mask:0xf
	v_fmac_f32_dpp v133, v121, v183 row_shl:14 row_mask:0xf bank_mask:0xf
	v_fmac_f32_dpp v134, v122, v184 row_shl:14 row_mask:0xf bank_mask:0xf
	v_fmac_f32_dpp v135, v123, v185 row_shl:14 row_mask:0xf bank_mask:0xf
	v_fmac_f32_dpp v136, v104, v198 row_shl:14 row_mask:0xf bank_mask:0xf
	v_fmac_f32_dpp v137, v105, v199 row_shl:14 row_mask:0xf bank_mask:0xf
	v_fmac_f32_dpp v138, v106, v200 row_shl:14 row_mask:0xf bank_mask:0xf
	v_fmac_f32_dpp v139, v107, v201 row_shl:14 row_mask:0xf bank_mask:0xf
	v_pk_mul_f32 v[140:141], v[132:133], v[132:133]
	v_pk_mul_f32 v[142:143], v[134:135], v[134:135]
	v_pk_fma_f32 v[140:141], v[140:141], s[98:99], v[244:245]
	v_pk_fma_f32 v[142:143], v[142:143], s[98:99], v[244:245]
	v_pk_mul_f32 v[140:141], v[132:133], v[140:141]
	v_pk_mul_f32 v[142:143], v[134:135], v[142:143]
	v_exp_f32_e32 v140, v140
	v_exp_f32_e32 v141, v141
	v_exp_f32_e32 v142, v142
	v_exp_f32_e32 v143, v143
	v_pk_add_f32 v[140:141], v[140:141], s[100:101]
	v_pk_add_f32 v[142:143], v[142:143], s[100:101]
	v_rcp_f32_e32 v140, v140
	v_rcp_f32_e32 v141, v141
	v_rcp_f32_e32 v142, v142
	v_rcp_f32_e32 v143, v143
	v_pk_mul_f32 v[140:141], v[132:133], v[140:141]
	v_pk_mul_f32 v[142:143], v[134:135], v[142:143]
	v_pk_mul_f32 v[140:141], v[140:141], v[136:137]
	v_pk_mul_f32 v[142:143], v[142:143], v[138:139]
	v_cvt_pk_bf16_f32 v252, v140, v141
	v_cvt_pk_bf16_f32 v253, v142, v143
	v_add_u32_e32 v144, 0x10, v248
	v_mad_u64_u32 v[144:145], vcc, v144, s4, v[242:243]
	global_store_dwordx4 v[144:145], v[250:253], off nt
	v_pk_fma_f32 v[132:133], v[100:101], v[158:159], v[146:147]
	v_pk_fma_f32 v[136:137], v[80:81], v[174:175], v[162:163]
	v_pk_fma_f32 v[134:135], v[102:103], v[160:161], v[148:149]
	v_pk_fma_f32 v[138:139], v[82:83], v[176:177], v[164:165]
	v_fmac_f32_dpp v132, v100, v154 row_shr:1 row_mask:0xf bank_mask:0xf
	v_fmac_f32_dpp v133, v101, v155 row_shr:1 row_mask:0xf bank_mask:0xf
	v_fmac_f32_dpp v134, v102, v156 row_shr:1 row_mask:0xf bank_mask:0xf
	v_fmac_f32_dpp v135, v103, v157 row_shr:1 row_mask:0xf bank_mask:0xf
	v_fmac_f32_dpp v136, v80, v170 row_shr:1 row_mask:0xf bank_mask:0xf
	v_fmac_f32_dpp v137, v81, v171 row_shr:1 row_mask:0xf bank_mask:0xf
	v_fmac_f32_dpp v138, v82, v172 row_shr:1 row_mask:0xf bank_mask:0xf
	v_fmac_f32_dpp v139, v83, v173 row_shr:1 row_mask:0xf bank_mask:0xf
	v_fmac_f32_dpp v132, v116, v154 row_shl:15 row_mask:0xf bank_mask:0xf
	v_fmac_f32_dpp v133, v117, v155 row_shl:15 row_mask:0xf bank_mask:0xf
	v_fmac_f32_dpp v134, v118, v156 row_shl:15 row_mask:0xf bank_mask:0xf
	v_fmac_f32_dpp v135, v119, v157 row_shl:15 row_mask:0xf bank_mask:0xf
	v_fmac_f32_dpp v136, v96, v170 row_shl:15 row_mask:0xf bank_mask:0xf
	v_fmac_f32_dpp v137, v97, v171 row_shl:15 row_mask:0xf bank_mask:0xf
	v_fmac_f32_dpp v138, v98, v172 row_shl:15 row_mask:0xf bank_mask:0xf
	v_fmac_f32_dpp v139, v99, v173 row_shl:15 row_mask:0xf bank_mask:0xf
	v_fmac_f32_dpp v132, v100, v150 row_shr:2 row_mask:0xf bank_mask:0xf
	v_fmac_f32_dpp v133, v101, v151 row_shr:2 row_mask:0xf bank_mask:0xf
	v_fmac_f32_dpp v134, v102, v152 row_shr:2 row_mask:0xf bank_mask:0xf
; __device__ __forceinline__ unsigned pk2(float lo, float hi) { unsigned r; asm("v_cvt_pk_bf16_f32 %0, %1, %2" : "=v"(r) : "v"(lo), "v"(hi)); return r; }
; __device__ __forceinline__ float gelu_tanh(float x) { const float y = 1.5957691216f * (x + 0.044715f * x * x * x); return x * __builtin_amdgcn_rcpf(1.0f + __expf(-y)); }
; __device__ __forceinline__ float dpp_shr1(float old, float src) { return __int_as_float(__builtin_amdgcn_update_dpp(__float_as_int(old), __float_as_int(src), 0x111, 0xf, 0xf, false)); }
; __device__ __forceinline__ float dpp_shr2(float old, float src) { return __int_as_float(__builtin_amdgcn_update_dpp(__float_as_int(old), __float_as_int(src), 0x112, 0xf, 0xf, false)); }
; __device__ __forceinline__ float dpp_ror1(float src) { return __int_as_float(__builtin_amdgcn_update_dpp(0, __float_as_int(src), 0x121, 0xf, 0xf, false)); }
;     __device__ __forceinline__ void operator()(const f32x4 (&acc)[2][2][4][2], const Unit& u, int wr, int wc, int fr, int fq) const {
;     ...
; #pragma unroll
;             for (int ai = 0; ai < 2; ++ai)
; #pragma unroll
;                 for (int m = 0; m < 4; ++m) { const int row = row0 + ai * HALF + m * 16;
;                     const f32x4 g0 = acc[ai][0][m][n], v0 = acc[ai][1][m][n];
;                     f32x4 gp = (f32x4){0.f, 0.f, 0.f, 0.f}, vp = gp;
;                     if (m > 0) { gp = acc[ai][0][m > 0 ? m - 1 : 0][n]; vp = acc[ai][1][m > 0 ? m - 1 : 0][n]; }
;                     f32x4 f;
; #pragma unroll
;                     for (int j = 0; j < 4; ++j) {
;                         const float g1 = dpp_shr1(dpp_ror1(gp[j]), g0[j]), g2 = dpp_shr2(dpp_ror2(gp[j]), g0[j]);
;                         const float v1 = dpp_shr1(dpp_ror1(vp[j]), v0[j]), v2 = dpp_shr2(dpp_ror2(vp[j]), v0[j]);
;                         const float cg_ = bg[j] + g2 * wg0[j] + g1 * wg1[j] + g0[j] * wg2[j];
;                         const float cv_ = bv[j] + v2 * wv0[j] + v1 * wv1[j] + v0[j] * wv2[j];
;                         f[j] = gelu_tanh(cg_) * cv_; }
;                     u32x2 w; w.x = pk2(f[0], f[1]); w.y = pk2(f[2], f[3]);
;                     if (n == 0) res0[ai * 4 + m] = w;
;                     else if (m > 0 || fr >= 2) { u32x4 w4; w4.x = res0[ai * 4 + m].x; w4.y = res0[ai * 4 + m].y; w4.z = w.x; w4.w = w.y; *(u32x4*)(F + (size_t)row * DFF + j0) = w4; }
	v_fmac_f32_dpp v135, v103, v153 row_shr:2 row_mask:0xf bank_mask:0xf
	v_fmac_f32_dpp v136, v80, v166 row_shr:2 row_mask:0xf bank_mask:0xf
	v_fmac_f32_dpp v137, v81, v167 row_shr:2 row_mask:0xf bank_mask:0xf
	v_fmac_f32_dpp v138, v82, v168 row_shr:2 row_mask:0xf bank_mask:0xf
	v_fmac_f32_dpp v139, v83, v169 row_shr:2 row_mask:0xf bank_mask:0xf
	v_fmac_f32_dpp v132, v116, v150 row_shl:14 row_mask:0xf bank_mask:0xf
	v_fmac_f32_dpp v133, v117, v151 row_shl:14 row_mask:0xf bank_mask:0xf
	v_fmac_f32_dpp v134, v118, v152 row_shl:14 row_mask:0xf bank_mask:0xf
	v_fmac_f32_dpp v135, v119, v153 row_shl:14 row_mask:0xf bank_mask:0xf
	v_fmac_f32_dpp v136, v96, v166 row_shl:14 row_mask:0xf bank_mask:0xf
	v_fmac_f32_dpp v137, v97, v167 row_shl:14 row_mask:0xf bank_mask:0xf
	v_fmac_f32_dpp v138, v98, v168 row_shl:14 row_mask:0xf bank_mask:0xf
	v_fmac_f32_dpp v139, v99, v169 row_shl:14 row_mask:0xf bank_mask:0xf
	v_pk_mul_f32 v[140:141], v[132:133], v[132:133]
	v_pk_mul_f32 v[142:143], v[134:135], v[134:135]
	v_pk_fma_f32 v[140:141], v[140:141], s[98:99], v[244:245]
	v_pk_fma_f32 v[142:143], v[142:143], s[98:99], v[244:245]
	v_pk_mul_f32 v[140:141], v[132:133], v[140:141]
	v_pk_mul_f32 v[142:143], v[134:135], v[142:143]
	v_exp_f32_e32 v140, v140
	v_exp_f32_e32 v141, v141
	v_exp_f32_e32 v142, v142
	v_exp_f32_e32 v143, v143
	v_pk_add_f32 v[140:141], v[140:141], s[100:101]
	v_pk_add_f32 v[142:143], v[142:143], s[100:101]
	v_rcp_f32_e32 v140, v140
	v_rcp_f32_e32 v141, v141
	v_rcp_f32_e32 v142, v142
	v_rcp_f32_e32 v143, v143
	v_pk_mul_f32 v[140:141], v[132:133], v[140:141]
	v_pk_mul_f32 v[142:143], v[134:135], v[142:143]
	v_pk_mul_f32 v[140:141], v[140:141], v[136:137]
	v_pk_mul_f32 v[142:143], v[142:143], v[138:139]
	v_cvt_pk_bf16_f32 v128, v140, v141
	v_cvt_pk_bf16_f32 v129, v142, v143
	v_pk_fma_f32 v[132:133], v[92:93], v[190:191], v[178:179]
	v_pk_fma_f32 v[136:137], v[72:73], v[206:207], v[194:195]
	v_pk_fma_f32 v[134:135], v[94:95], v[192:193], v[180:181]
	v_pk_fma_f32 v[138:139], v[74:75], v[208:209], v[196:197]
	v_fmac_f32_dpp v132, v92, v186 row_shr:1 row_mask:0xf bank_mask:0xf
	v_fmac_f32_dpp v133, v93, v187 row_shr:1 row_mask:0xf bank_mask:0xf
	v_fmac_f32_dpp v134, v94, v188 row_shr:1 row_mask:0xf bank_mask:0xf
	v_fmac_f32_dpp v135, v95, v189 row_shr:1 row_mask:0xf bank_mask:0xf
	v_fmac_f32_dpp v136, v72, v202 row_shr:1 row_mask:0xf bank_mask:0xf
	v_fmac_f32_dpp v137, v73, v203 row_shr:1 row_mask:0xf bank_mask:0xf
	v_fmac_f32_dpp v138, v74, v204 row_shr:1 row_mask:0xf bank_mask:0xf
	v_fmac_f32_dpp v139, v75, v205 row_shr:1 row_mask:0xf bank_mask:0xf
	v_fmac_f32_dpp v132, v108, v186 row_shl:15 row_mask:0xf bank_mask:0xf
	v_fmac_f32_dpp v133, v109, v187 row_shl:15 row_mask:0xf bank_mask:0xf
	v_fmac_f32_dpp v134, v110, v188 row_shl:15 row_mask:0xf bank_mask:0xf
	v_fmac_f32_dpp v135, v111, v189 row_shl:15 row_mask:0xf bank_mask:0xf
	v_fmac_f32_dpp v136, v88, v202 row_shl:15 row_mask:0xf bank_mask:0xf
	v_fmac_f32_dpp v137, v89, v203 row_shl:15 row_mask:0xf bank_mask:0xf
	v_fmac_f32_dpp v138, v90, v204 row_shl:15 row_mask:0xf bank_mask:0xf
	v_fmac_f32_dpp v139, v91, v205 row_shl:15 row_mask:0xf bank_mask:0xf
	v_fmac_f32_dpp v132, v92, v182 row_shr:2 row_mask:0xf bank_mask:0xf
	v_fmac_f32_dpp v133, v93, v183 row_shr:2 row_mask:0xf bank_mask:0xf
	v_fmac_f32_dpp v134, v94, v184 row_shr:2 row_mask:0xf bank_mask:0xf
	v_fmac_f32_dpp v135, v95, v185 row_shr:2 row_mask:0xf bank_mask:0xf
	v_fmac_f32_dpp v136, v72, v198 row_shr:2 row_mask:0xf bank_mask:0xf
	v_fmac_f32_dpp v137, v73, v199 row_shr:2 row_mask:0xf bank_mask:0xf
	v_fmac_f32_dpp v138, v74, v200 row_shr:2 row_mask:0xf bank_mask:0xf
	v_fmac_f32_dpp v139, v75, v201 row_shr:2 row_mask:0xf bank_mask:0xf
	v_fmac_f32_dpp v132, v108, v182 row_shl:14 row_mask:0xf bank_mask:0xf
	v_fmac_f32_dpp v133, v109, v183 row_shl:14 row_mask:0xf bank_mask:0xf
	v_fmac_f32_dpp v134, v110, v184 row_shl:14 row_mask:0xf bank_mask:0xf
	v_fmac_f32_dpp v135, v111, v185 row_shl:14 row_mask:0xf bank_mask:0xf
	v_fmac_f32_dpp v136, v88, v198 row_shl:14 row_mask:0xf bank_mask:0xf
	v_fmac_f32_dpp v137, v89, v199 row_shl:14 row_mask:0xf bank_mask:0xf
	v_fmac_f32_dpp v138, v90, v200 row_shl:14 row_mask:0xf bank_mask:0xf
	v_fmac_f32_dpp v139, v91, v201 row_shl:14 row_mask:0xf bank_mask:0xf
	v_pk_mul_f32 v[140:141], v[132:133], v[132:133]
	v_pk_mul_f32 v[142:143], v[134:135], v[134:135]
	v_pk_fma_f32 v[140:141], v[140:141], s[98:99], v[244:245]
	v_pk_fma_f32 v[142:143], v[142:143], s[98:99], v[244:245]
	v_pk_mul_f32 v[140:141], v[132:133], v[140:141]
	v_pk_mul_f32 v[142:143], v[134:135], v[142:143]
	v_exp_f32_e32 v140, v140
	v_exp_f32_e32 v141, v141
	v_exp_f32_e32 v142, v142
	v_exp_f32_e32 v143, v143
	v_pk_add_f32 v[140:141], v[140:141], s[100:101]
	v_pk_add_f32 v[142:143], v[142:143], s[100:101]
	v_rcp_f32_e32 v140, v140
	v_rcp_f32_e32 v141, v141
	v_rcp_f32_e32 v142, v142
	v_rcp_f32_e32 v143, v143
	v_pk_mul_f32 v[140:141], v[132:133], v[140:141]
	v_pk_mul_f32 v[142:143], v[134:135], v[142:143]
	v_pk_mul_f32 v[140:141], v[140:141], v[136:137]
	v_pk_mul_f32 v[142:143], v[142:143], v[138:139]
	v_cvt_pk_bf16_f32 v130, v140, v141
	v_cvt_pk_bf16_f32 v131, v142, v143
	v_add_u32_e32 v144, 0x20, v248
	v_mad_u64_u32 v[144:145], vcc, v144, s4, v[242:243]
	global_store_dwordx4 v[144:145], v[128:131], off nt
	v_pk_fma_f32 v[132:133], v[84:85], v[158:159], v[146:147]
	v_pk_fma_f32 v[136:137], v[68:69], v[174:175], v[162:163]
	v_pk_fma_f32 v[134:135], v[86:87], v[160:161], v[148:149]
	v_pk_fma_f32 v[138:139], v[70:71], v[176:177], v[164:165]
	v_fmac_f32_dpp v132, v84, v154 row_shr:1 row_mask:0xf bank_mask:0xf
	v_fmac_f32_dpp v133, v85, v155 row_shr:1 row_mask:0xf bank_mask:0xf
; __device__ __forceinline__ unsigned pk2(float lo, float hi) { unsigned r; asm("v_cvt_pk_bf16_f32 %0, %1, %2" : "=v"(r) : "v"(lo), "v"(hi)); return r; }
;     __device__ __forceinline__ void operator()(const f32x4 (&acc)[2][2][4][2], const Unit& u, int wr, int wc, int fr, int fq) const {
;     ...
; #pragma unroll
;             for (int ai = 0; ai < 2; ++ai)
; #pragma unroll
;                 for (int m = 0; m < 4; ++m) { const int row = row0 + ai * HALF + m * 16;
;                     const f32x4 g0 = acc[ai][0][m][n], v0 = acc[ai][1][m][n];
;                     f32x4 gp = (f32x4){0.f, 0.f, 0.f, 0.f}, vp = gp;
;                     if (m > 0) { gp = acc[ai][0][m > 0 ? m - 1 : 0][n]; vp = acc[ai][1][m > 0 ? m - 1 : 0][n]; }
;                     f32x4 f;
; #pragma unroll
;                     for (int j = 0; j < 4; ++j) {
;                         const float g1 = dpp_shr1(dpp_ror1(gp[j]), g0[j]), g2 = dpp_shr2(dpp_ror2(gp[j]), g0[j]);
;                         const float v1 = dpp_shr1(dpp_ror1(vp[j]), v0[j]), v2 = dpp_shr2(dpp_ror2(vp[j]), v0[j]);
;                         const float cg_ = bg[j] + g2 * wg0[j] + g1 * wg1[j] + g0[j] * wg2[j];
;                         const float cv_ = bv[j] + v2 * wv0[j] + v1 * wv1[j] + v0[j] * wv2[j];
;                         f[j] = gelu_tanh(cg_) * cv_; }
;                     u32x2 w; w.x = pk2(f[0], f[1]); w.y = pk2(f[2], f[3]);
;                     if (n == 0) res0[ai * 4 + m] = w;
;                     else if (m > 0 || fr >= 2) { u32x4 w4; w4.x = res0[ai * 4 + m].x; w4.y = res0[ai * 4 + m].y; w4.z = w.x; w4.w = w.y; *(u32x4*)(F + (size_t)row * DFF + j0) = w4; }
;                     if (n == 1 && ((m == 0 && fr < 2) || (m == 3 && fr >= 14))) { const int slot = m == 0 ? fr : fr - 12;
;                         const f32x4 ga = acc[ai][0][m][0], va = acc[ai][1][m][0];
;                         bf16_t* bp = UPB + ((size_t)(row >> 6) * 4 + slot) * (2 * DFF) + col0;
;                         u32x4 wg_, wv_; wg_.x = pk2(ga[0], ga[1]); wg_.y = pk2(ga[2], ga[3]); wg_.z = pk2(g0[0], g0[1]); wg_.w = pk2(g0[2], g0[3]);
;                         wv_.x = pk2(va[0], va[1]); wv_.y = pk2(va[2], va[3]); wv_.z = pk2(v0[0], v0[1]); wv_.w = pk2(v0[2], v0[3]);
;                         *(u32x4*)bp = wg_; *(u32x4*)(bp + HALF) = wv_; } }
	v_fmac_f32_dpp v134, v86, v156 row_shr:1 row_mask:0xf bank_mask:0xf
	v_fmac_f32_dpp v135, v87, v157 row_shr:1 row_mask:0xf bank_mask:0xf
	v_fmac_f32_dpp v136, v68, v170 row_shr:1 row_mask:0xf bank_mask:0xf
	v_fmac_f32_dpp v137, v69, v171 row_shr:1 row_mask:0xf bank_mask:0xf
	v_fmac_f32_dpp v138, v70, v172 row_shr:1 row_mask:0xf bank_mask:0xf
	v_fmac_f32_dpp v139, v71, v173 row_shr:1 row_mask:0xf bank_mask:0xf
	v_fmac_f32_dpp v132, v100, v154 row_shl:15 row_mask:0xf bank_mask:0xf
	v_fmac_f32_dpp v133, v101, v155 row_shl:15 row_mask:0xf bank_mask:0xf
	v_fmac_f32_dpp v134, v102, v156 row_shl:15 row_mask:0xf bank_mask:0xf
	v_fmac_f32_dpp v135, v103, v157 row_shl:15 row_mask:0xf bank_mask:0xf
	v_fmac_f32_dpp v136, v80, v170 row_shl:15 row_mask:0xf bank_mask:0xf
	v_fmac_f32_dpp v137, v81, v171 row_shl:15 row_mask:0xf bank_mask:0xf
	v_fmac_f32_dpp v138, v82, v172 row_shl:15 row_mask:0xf bank_mask:0xf
	v_fmac_f32_dpp v139, v83, v173 row_shl:15 row_mask:0xf bank_mask:0xf
	v_fmac_f32_dpp v132, v84, v150 row_shr:2 row_mask:0xf bank_mask:0xf
	v_fmac_f32_dpp v133, v85, v151 row_shr:2 row_mask:0xf bank_mask:0xf
	v_fmac_f32_dpp v134, v86, v152 row_shr:2 row_mask:0xf bank_mask:0xf
	v_fmac_f32_dpp v135, v87, v153 row_shr:2 row_mask:0xf bank_mask:0xf
	v_fmac_f32_dpp v136, v68, v166 row_shr:2 row_mask:0xf bank_mask:0xf
	v_fmac_f32_dpp v137, v69, v167 row_shr:2 row_mask:0xf bank_mask:0xf
	v_fmac_f32_dpp v138, v70, v168 row_shr:2 row_mask:0xf bank_mask:0xf
	v_fmac_f32_dpp v139, v71, v169 row_shr:2 row_mask:0xf bank_mask:0xf
	v_fmac_f32_dpp v132, v100, v150 row_shl:14 row_mask:0xf bank_mask:0xf
	v_fmac_f32_dpp v133, v101, v151 row_shl:14 row_mask:0xf bank_mask:0xf
	v_fmac_f32_dpp v134, v102, v152 row_shl:14 row_mask:0xf bank_mask:0xf
	v_fmac_f32_dpp v135, v103, v153 row_shl:14 row_mask:0xf bank_mask:0xf
	v_fmac_f32_dpp v136, v80, v166 row_shl:14 row_mask:0xf bank_mask:0xf
	v_fmac_f32_dpp v137, v81, v167 row_shl:14 row_mask:0xf bank_mask:0xf
	v_fmac_f32_dpp v138, v82, v168 row_shl:14 row_mask:0xf bank_mask:0xf
	v_fmac_f32_dpp v139, v83, v169 row_shl:14 row_mask:0xf bank_mask:0xf
	v_pk_mul_f32 v[140:141], v[132:133], v[132:133]
	v_pk_mul_f32 v[142:143], v[134:135], v[134:135]
	v_pk_fma_f32 v[140:141], v[140:141], s[98:99], v[244:245]
	v_pk_fma_f32 v[142:143], v[142:143], s[98:99], v[244:245]
	v_pk_mul_f32 v[140:141], v[132:133], v[140:141]
	v_pk_mul_f32 v[142:143], v[134:135], v[142:143]
	v_exp_f32_e32 v140, v140
	v_exp_f32_e32 v141, v141
	v_exp_f32_e32 v142, v142
	v_exp_f32_e32 v143, v143
	v_pk_add_f32 v[140:141], v[140:141], s[100:101]
	v_pk_add_f32 v[142:143], v[142:143], s[100:101]
	v_rcp_f32_e32 v140, v140
	v_rcp_f32_e32 v141, v141
	v_rcp_f32_e32 v142, v142
	v_rcp_f32_e32 v143, v143
	v_pk_mul_f32 v[140:141], v[132:133], v[140:141]
	v_pk_mul_f32 v[142:143], v[134:135], v[142:143]
	v_pk_mul_f32 v[140:141], v[140:141], v[136:137]
	v_pk_mul_f32 v[142:143], v[142:143], v[138:139]
	v_cvt_pk_bf16_f32 v250, v140, v141
	v_cvt_pk_bf16_f32 v251, v142, v143
	v_pk_fma_f32 v[132:133], v[76:77], v[190:191], v[178:179]
	v_pk_fma_f32 v[136:137], v[64:65], v[206:207], v[194:195]
	v_pk_fma_f32 v[134:135], v[78:79], v[192:193], v[180:181]
	v_pk_fma_f32 v[138:139], v[66:67], v[208:209], v[196:197]
	v_fmac_f32_dpp v132, v76, v186 row_shr:1 row_mask:0xf bank_mask:0xf
	v_fmac_f32_dpp v133, v77, v187 row_shr:1 row_mask:0xf bank_mask:0xf
	v_fmac_f32_dpp v134, v78, v188 row_shr:1 row_mask:0xf bank_mask:0xf
	v_fmac_f32_dpp v135, v79, v189 row_shr:1 row_mask:0xf bank_mask:0xf
	v_fmac_f32_dpp v136, v64, v202 row_shr:1 row_mask:0xf bank_mask:0xf
	v_fmac_f32_dpp v137, v65, v203 row_shr:1 row_mask:0xf bank_mask:0xf
	v_fmac_f32_dpp v138, v66, v204 row_shr:1 row_mask:0xf bank_mask:0xf
	v_fmac_f32_dpp v139, v67, v205 row_shr:1 row_mask:0xf bank_mask:0xf
	v_fmac_f32_dpp v132, v92, v186 row_shl:15 row_mask:0xf bank_mask:0xf
	v_fmac_f32_dpp v133, v93, v187 row_shl:15 row_mask:0xf bank_mask:0xf
	v_fmac_f32_dpp v134, v94, v188 row_shl:15 row_mask:0xf bank_mask:0xf
	v_fmac_f32_dpp v135, v95, v189 row_shl:15 row_mask:0xf bank_mask:0xf
	v_fmac_f32_dpp v136, v72, v202 row_shl:15 row_mask:0xf bank_mask:0xf
	v_fmac_f32_dpp v137, v73, v203 row_shl:15 row_mask:0xf bank_mask:0xf
	v_fmac_f32_dpp v138, v74, v204 row_shl:15 row_mask:0xf bank_mask:0xf
	v_fmac_f32_dpp v139, v75, v205 row_shl:15 row_mask:0xf bank_mask:0xf
	v_fmac_f32_dpp v132, v76, v182 row_shr:2 row_mask:0xf bank_mask:0xf
	v_fmac_f32_dpp v133, v77, v183 row_shr:2 row_mask:0xf bank_mask:0xf
	v_fmac_f32_dpp v134, v78, v184 row_shr:2 row_mask:0xf bank_mask:0xf
	v_fmac_f32_dpp v135, v79, v185 row_shr:2 row_mask:0xf bank_mask:0xf
	v_fmac_f32_dpp v136, v64, v198 row_shr:2 row_mask:0xf bank_mask:0xf
	v_fmac_f32_dpp v137, v65, v199 row_shr:2 row_mask:0xf bank_mask:0xf
	v_fmac_f32_dpp v138, v66, v200 row_shr:2 row_mask:0xf bank_mask:0xf
	v_fmac_f32_dpp v139, v67, v201 row_shr:2 row_mask:0xf bank_mask:0xf
	v_fmac_f32_dpp v132, v92, v182 row_shl:14 row_mask:0xf bank_mask:0xf
	v_fmac_f32_dpp v133, v93, v183 row_shl:14 row_mask:0xf bank_mask:0xf
	v_fmac_f32_dpp v134, v94, v184 row_shl:14 row_mask:0xf bank_mask:0xf
	v_fmac_f32_dpp v135, v95, v185 row_shl:14 row_mask:0xf bank_mask:0xf
	v_fmac_f32_dpp v136, v72, v198 row_shl:14 row_mask:0xf bank_mask:0xf
	v_fmac_f32_dpp v137, v73, v199 row_shl:14 row_mask:0xf bank_mask:0xf
	v_fmac_f32_dpp v138, v74, v200 row_shl:14 row_mask:0xf bank_mask:0xf
	v_fmac_f32_dpp v139, v75, v201 row_shl:14 row_mask:0xf bank_mask:0xf
	v_pk_mul_f32 v[140:141], v[132:133], v[132:133]
	v_pk_mul_f32 v[142:143], v[134:135], v[134:135]
	v_pk_fma_f32 v[140:141], v[140:141], s[98:99], v[244:245]
	v_pk_fma_f32 v[142:143], v[142:143], s[98:99], v[244:245]
; __device__ __forceinline__ unsigned pk2(float lo, float hi) { unsigned r; asm("v_cvt_pk_bf16_f32 %0, %1, %2" : "=v"(r) : "v"(lo), "v"(hi)); return r; }
;     __device__ __forceinline__ void operator()(const f32x4 (&acc)[2][2][4][2], const Unit& u, int wr, int wc, int fr, int fq) const {
;     ...
; #pragma unroll
;             for (int ai = 0; ai < 2; ++ai)
; #pragma unroll
;                 for (int m = 0; m < 4; ++m) { const int row = row0 + ai * HALF + m * 16;
;                     const f32x4 g0 = acc[ai][0][m][n], v0 = acc[ai][1][m][n];
;                     f32x4 gp = (f32x4){0.f, 0.f, 0.f, 0.f}, vp = gp;
;                     if (m > 0) { gp = acc[ai][0][m > 0 ? m - 1 : 0][n]; vp = acc[ai][1][m > 0 ? m - 1 : 0][n]; }
;                     f32x4 f;
; #pragma unroll
;                     for (int j = 0; j < 4; ++j) {
;                         const float g1 = dpp_shr1(dpp_ror1(gp[j]), g0[j]), g2 = dpp_shr2(dpp_ror2(gp[j]), g0[j]);
;                         const float v1 = dpp_shr1(dpp_ror1(vp[j]), v0[j]), v2 = dpp_shr2(dpp_ror2(vp[j]), v0[j]);
;                         const float cg_ = bg[j] + g2 * wg0[j] + g1 * wg1[j] + g0[j] * wg2[j];
;                         const float cv_ = bv[j] + v2 * wv0[j] + v1 * wv1[j] + v0[j] * wv2[j];
;                         f[j] = gelu_tanh(cg_) * cv_; }
;                     u32x2 w; w.x = pk2(f[0], f[1]); w.y = pk2(f[2], f[3]);
;                     if (n == 0) res0[ai * 4 + m] = w;
;                     else if (m > 0 || fr >= 2) { u32x4 w4; w4.x = res0[ai * 4 + m].x; w4.y = res0[ai * 4 + m].y; w4.z = w.x; w4.w = w.y; *(u32x4*)(F + (size_t)row * DFF + j0) = w4; }
;                     if (n == 1 && ((m == 0 && fr < 2) || (m == 3 && fr >= 14))) { const int slot = m == 0 ? fr : fr - 12;
;                         const f32x4 ga = acc[ai][0][m][0], va = acc[ai][1][m][0];
;                         bf16_t* bp = UPB + ((size_t)(row >> 6) * 4 + slot) * (2 * DFF) + col0;
;                         u32x4 wg_, wv_; wg_.x = pk2(ga[0], ga[1]); wg_.y = pk2(ga[2], ga[3]); wg_.z = pk2(g0[0], g0[1]); wg_.w = pk2(g0[2], g0[3]);
;                         wv_.x = pk2(va[0], va[1]); wv_.y = pk2(va[2], va[3]); wv_.z = pk2(v0[0], v0[1]); wv_.w = pk2(v0[2], v0[3]);
;                         *(u32x4*)bp = wg_; *(u32x4*)(bp + HALF) = wv_; } }
	v_pk_mul_f32 v[140:141], v[132:133], v[140:141]
	v_pk_mul_f32 v[142:143], v[134:135], v[142:143]
	v_exp_f32_e32 v140, v140
	v_exp_f32_e32 v141, v141
	v_exp_f32_e32 v142, v142
	v_exp_f32_e32 v143, v143
	v_pk_add_f32 v[140:141], v[140:141], s[100:101]
	v_pk_add_f32 v[142:143], v[142:143], s[100:101]
	v_rcp_f32_e32 v140, v140
	v_rcp_f32_e32 v141, v141
	v_rcp_f32_e32 v142, v142
	v_rcp_f32_e32 v143, v143
	v_pk_mul_f32 v[140:141], v[132:133], v[140:141]
	v_pk_mul_f32 v[142:143], v[134:135], v[142:143]
	v_pk_mul_f32 v[140:141], v[140:141], v[136:137]
	v_pk_mul_f32 v[142:143], v[142:143], v[138:139]
	v_cvt_pk_bf16_f32 v252, v140, v141
	v_cvt_pk_bf16_f32 v253, v142, v143
	v_add_u32_e32 v144, 0x30, v248
	v_mad_u64_u32 v[144:145], vcc, v144, s4, v[242:243]
	global_store_dwordx4 v[144:145], v[250:253], off nt
	v_pk_fma_f32 v[132:133], v[60:61], v[158:159], v[146:147]
	v_pk_fma_f32 v[136:137], v[48:49], v[174:175], v[162:163]
	v_pk_fma_f32 v[134:135], v[62:63], v[160:161], v[148:149]
	v_pk_fma_f32 v[138:139], v[50:51], v[176:177], v[164:165]
	v_fmac_f32_dpp v132, v60, v154 row_shr:1 row_mask:0xf bank_mask:0xf
	v_fmac_f32_dpp v133, v61, v155 row_shr:1 row_mask:0xf bank_mask:0xf
	v_fmac_f32_dpp v134, v62, v156 row_shr:1 row_mask:0xf bank_mask:0xf
	v_fmac_f32_dpp v135, v63, v157 row_shr:1 row_mask:0xf bank_mask:0xf
	v_fmac_f32_dpp v136, v48, v170 row_shr:1 row_mask:0xf bank_mask:0xf
	v_fmac_f32_dpp v137, v49, v171 row_shr:1 row_mask:0xf bank_mask:0xf
	v_fmac_f32_dpp v138, v50, v172 row_shr:1 row_mask:0xf bank_mask:0xf
	v_fmac_f32_dpp v139, v51, v173 row_shr:1 row_mask:0xf bank_mask:0xf
	v_fmac_f32_dpp v132, v60, v150 row_shr:2 row_mask:0xf bank_mask:0xf
	v_fmac_f32_dpp v133, v61, v151 row_shr:2 row_mask:0xf bank_mask:0xf
	v_fmac_f32_dpp v134, v62, v152 row_shr:2 row_mask:0xf bank_mask:0xf
	v_fmac_f32_dpp v135, v63, v153 row_shr:2 row_mask:0xf bank_mask:0xf
	v_fmac_f32_dpp v136, v48, v166 row_shr:2 row_mask:0xf bank_mask:0xf
	v_fmac_f32_dpp v137, v49, v167 row_shr:2 row_mask:0xf bank_mask:0xf
	v_fmac_f32_dpp v138, v50, v168 row_shr:2 row_mask:0xf bank_mask:0xf
	v_fmac_f32_dpp v139, v51, v169 row_shr:2 row_mask:0xf bank_mask:0xf
	v_pk_mul_f32 v[140:141], v[132:133], v[132:133]
	v_pk_mul_f32 v[142:143], v[134:135], v[134:135]
	v_pk_fma_f32 v[140:141], v[140:141], s[98:99], v[244:245]
	v_pk_fma_f32 v[142:143], v[142:143], s[98:99], v[244:245]
	v_pk_mul_f32 v[140:141], v[132:133], v[140:141]
	v_pk_mul_f32 v[142:143], v[134:135], v[142:143]
	v_exp_f32_e32 v140, v140
	v_exp_f32_e32 v141, v141
	v_exp_f32_e32 v142, v142
	v_exp_f32_e32 v143, v143
	v_pk_add_f32 v[140:141], v[140:141], s[100:101]
	v_pk_add_f32 v[142:143], v[142:143], s[100:101]
	v_rcp_f32_e32 v140, v140
	v_rcp_f32_e32 v141, v141
	v_rcp_f32_e32 v142, v142
	v_rcp_f32_e32 v143, v143
	v_pk_mul_f32 v[140:141], v[132:133], v[140:141]
	v_pk_mul_f32 v[142:143], v[134:135], v[142:143]
	v_pk_mul_f32 v[140:141], v[140:141], v[136:137]
	v_pk_mul_f32 v[142:143], v[142:143], v[138:139]
	v_cvt_pk_bf16_f32 v128, v140, v141
	v_cvt_pk_bf16_f32 v129, v142, v143
	v_pk_fma_f32 v[132:133], v[56:57], v[190:191], v[178:179]
	v_pk_fma_f32 v[136:137], v[40:41], v[206:207], v[194:195]
	v_pk_fma_f32 v[134:135], v[58:59], v[192:193], v[180:181]
	v_pk_fma_f32 v[138:139], v[42:43], v[208:209], v[196:197]
	v_fmac_f32_dpp v132, v56, v186 row_shr:1 row_mask:0xf bank_mask:0xf
	v_fmac_f32_dpp v133, v57, v187 row_shr:1 row_mask:0xf bank_mask:0xf
	v_fmac_f32_dpp v134, v58, v188 row_shr:1 row_mask:0xf bank_mask:0xf
	v_fmac_f32_dpp v135, v59, v189 row_shr:1 row_mask:0xf bank_mask:0xf
	v_fmac_f32_dpp v136, v40, v202 row_shr:1 row_mask:0xf bank_mask:0xf
	v_fmac_f32_dpp v137, v41, v203 row_shr:1 row_mask:0xf bank_mask:0xf
	v_fmac_f32_dpp v138, v42, v204 row_shr:1 row_mask:0xf bank_mask:0xf
	v_fmac_f32_dpp v139, v43, v205 row_shr:1 row_mask:0xf bank_mask:0xf
	v_fmac_f32_dpp v132, v56, v182 row_shr:2 row_mask:0xf bank_mask:0xf
	v_fmac_f32_dpp v133, v57, v183 row_shr:2 row_mask:0xf bank_mask:0xf
	v_fmac_f32_dpp v134, v58, v184 row_shr:2 row_mask:0xf bank_mask:0xf
	v_fmac_f32_dpp v135, v59, v185 row_shr:2 row_mask:0xf bank_mask:0xf
	v_fmac_f32_dpp v136, v40, v198 row_shr:2 row_mask:0xf bank_mask:0xf
	v_fmac_f32_dpp v137, v41, v199 row_shr:2 row_mask:0xf bank_mask:0xf
	v_fmac_f32_dpp v138, v42, v200 row_shr:2 row_mask:0xf bank_mask:0xf
	v_fmac_f32_dpp v139, v43, v201 row_shr:2 row_mask:0xf bank_mask:0xf
	v_pk_mul_f32 v[140:141], v[132:133], v[132:133]
	v_pk_mul_f32 v[142:143], v[134:135], v[134:135]
	v_pk_fma_f32 v[140:141], v[140:141], s[98:99], v[244:245]
	v_pk_fma_f32 v[142:143], v[142:143], s[98:99], v[244:245]
	v_pk_mul_f32 v[140:141], v[132:133], v[140:141]
	v_pk_mul_f32 v[142:143], v[134:135], v[142:143]
	v_exp_f32_e32 v140, v140
	v_exp_f32_e32 v141, v141
	v_exp_f32_e32 v142, v142
	v_exp_f32_e32 v143, v143
	v_pk_add_f32 v[140:141], v[140:141], s[100:101]
	v_pk_add_f32 v[142:143], v[142:143], s[100:101]
	v_rcp_f32_e32 v140, v140
	v_rcp_f32_e32 v141, v141
	v_rcp_f32_e32 v142, v142
	v_rcp_f32_e32 v143, v143
	v_pk_mul_f32 v[140:141], v[132:133], v[140:141]
	v_pk_mul_f32 v[142:143], v[134:135], v[142:143]
	v_pk_mul_f32 v[140:141], v[140:141], v[136:137]
	v_pk_mul_f32 v[142:143], v[142:143], v[138:139]
	v_cvt_pk_bf16_f32 v130, v140, v141
	v_cvt_pk_bf16_f32 v131, v142, v143
	s_and_saveexec_b64 s[42:43], s[8:9]
	v_add_u32_e32 v144, 0x80, v248
	v_mad_u64_u32 v[144:145], vcc, v144, s4, v[242:243]
	global_store_dwordx4 v[144:145], v[128:131], off nt
	s_or_b64 exec, exec, s[42:43]
	s_nop 4
	v_pk_fma_f32 v[132:133], v[52:53], v[158:159], v[146:147]
	v_pk_fma_f32 v[136:137], v[32:33], v[174:175], v[162:163]
	v_pk_fma_f32 v[134:135], v[54:55], v[160:161], v[148:149]
; __device__ __forceinline__ unsigned pk2(float lo, float hi) { unsigned r; asm("v_cvt_pk_bf16_f32 %0, %1, %2" : "=v"(r) : "v"(lo), "v"(hi)); return r; }
;     __device__ __forceinline__ void operator()(const f32x4 (&acc)[2][2][4][2], const Unit& u, int wr, int wc, int fr, int fq) const {
;     ...
; #pragma unroll
;             for (int ai = 0; ai < 2; ++ai)
; #pragma unroll
;                 for (int m = 0; m < 4; ++m) { const int row = row0 + ai * HALF + m * 16;
;                     const f32x4 g0 = acc[ai][0][m][n], v0 = acc[ai][1][m][n];
;                     f32x4 gp = (f32x4){0.f, 0.f, 0.f, 0.f}, vp = gp;
;                     if (m > 0) { gp = acc[ai][0][m > 0 ? m - 1 : 0][n]; vp = acc[ai][1][m > 0 ? m - 1 : 0][n]; }
;                     f32x4 f;
; #pragma unroll
;                     for (int j = 0; j < 4; ++j) {
;                         const float g1 = dpp_shr1(dpp_ror1(gp[j]), g0[j]), g2 = dpp_shr2(dpp_ror2(gp[j]), g0[j]);
;                         const float v1 = dpp_shr1(dpp_ror1(vp[j]), v0[j]), v2 = dpp_shr2(dpp_ror2(vp[j]), v0[j]);
;                         const float cg_ = bg[j] + g2 * wg0[j] + g1 * wg1[j] + g0[j] * wg2[j];
;                         const float cv_ = bv[j] + v2 * wv0[j] + v1 * wv1[j] + v0[j] * wv2[j];
;                         f[j] = gelu_tanh(cg_) * cv_; }
;                     u32x2 w; w.x = pk2(f[0], f[1]); w.y = pk2(f[2], f[3]);
;                     if (n == 0) res0[ai * 4 + m] = w;
;                     else if (m > 0 || fr >= 2) { u32x4 w4; w4.x = res0[ai * 4 + m].x; w4.y = res0[ai * 4 + m].y; w4.z = w.x; w4.w = w.y; *(u32x4*)(F + (size_t)row * DFF + j0) = w4; }
;                     if (n == 1 && ((m == 0 && fr < 2) || (m == 3 && fr >= 14))) { const int slot = m == 0 ? fr : fr - 12;
;                         const f32x4 ga = acc[ai][0][m][0], va = acc[ai][1][m][0];
;                         bf16_t* bp = UPB + ((size_t)(row >> 6) * 4 + slot) * (2 * DFF) + col0;
;                         u32x4 wg_, wv_; wg_.x = pk2(ga[0], ga[1]); wg_.y = pk2(ga[2], ga[3]); wg_.z = pk2(g0[0], g0[1]); wg_.w = pk2(g0[2], g0[3]);
;                         wv_.x = pk2(va[0], va[1]); wv_.y = pk2(va[2], va[3]); wv_.z = pk2(v0[0], v0[1]); wv_.w = pk2(v0[2], v0[3]);
;                         *(u32x4*)bp = wg_; *(u32x4*)(bp + HALF) = wv_; } }
	v_pk_fma_f32 v[138:139], v[34:35], v[176:177], v[164:165]
	v_fmac_f32_dpp v132, v52, v154 row_shr:1 row_mask:0xf bank_mask:0xf
	v_fmac_f32_dpp v133, v53, v155 row_shr:1 row_mask:0xf bank_mask:0xf
	v_fmac_f32_dpp v134, v54, v156 row_shr:1 row_mask:0xf bank_mask:0xf
	v_fmac_f32_dpp v135, v55, v157 row_shr:1 row_mask:0xf bank_mask:0xf
	v_fmac_f32_dpp v136, v32, v170 row_shr:1 row_mask:0xf bank_mask:0xf
	v_fmac_f32_dpp v137, v33, v171 row_shr:1 row_mask:0xf bank_mask:0xf
	v_fmac_f32_dpp v138, v34, v172 row_shr:1 row_mask:0xf bank_mask:0xf
	v_fmac_f32_dpp v139, v35, v173 row_shr:1 row_mask:0xf bank_mask:0xf
	v_fmac_f32_dpp v132, v60, v154 row_shl:15 row_mask:0xf bank_mask:0xf
	v_fmac_f32_dpp v133, v61, v155 row_shl:15 row_mask:0xf bank_mask:0xf
	v_fmac_f32_dpp v134, v62, v156 row_shl:15 row_mask:0xf bank_mask:0xf
	v_fmac_f32_dpp v135, v63, v157 row_shl:15 row_mask:0xf bank_mask:0xf
	v_fmac_f32_dpp v136, v48, v170 row_shl:15 row_mask:0xf bank_mask:0xf
	v_fmac_f32_dpp v137, v49, v171 row_shl:15 row_mask:0xf bank_mask:0xf
	v_fmac_f32_dpp v138, v50, v172 row_shl:15 row_mask:0xf bank_mask:0xf
	v_fmac_f32_dpp v139, v51, v173 row_shl:15 row_mask:0xf bank_mask:0xf
	v_fmac_f32_dpp v132, v52, v150 row_shr:2 row_mask:0xf bank_mask:0xf
	v_fmac_f32_dpp v133, v53, v151 row_shr:2 row_mask:0xf bank_mask:0xf
	v_fmac_f32_dpp v134, v54, v152 row_shr:2 row_mask:0xf bank_mask:0xf
	v_fmac_f32_dpp v135, v55, v153 row_shr:2 row_mask:0xf bank_mask:0xf
	v_fmac_f32_dpp v136, v32, v166 row_shr:2 row_mask:0xf bank_mask:0xf
	v_fmac_f32_dpp v137, v33, v167 row_shr:2 row_mask:0xf bank_mask:0xf
	v_fmac_f32_dpp v138, v34, v168 row_shr:2 row_mask:0xf bank_mask:0xf
	v_fmac_f32_dpp v139, v35, v169 row_shr:2 row_mask:0xf bank_mask:0xf
	v_fmac_f32_dpp v132, v60, v150 row_shl:14 row_mask:0xf bank_mask:0xf
	v_fmac_f32_dpp v133, v61, v151 row_shl:14 row_mask:0xf bank_mask:0xf
	v_fmac_f32_dpp v134, v62, v152 row_shl:14 row_mask:0xf bank_mask:0xf
	v_fmac_f32_dpp v135, v63, v153 row_shl:14 row_mask:0xf bank_mask:0xf
	v_fmac_f32_dpp v136, v48, v166 row_shl:14 row_mask:0xf bank_mask:0xf
	v_fmac_f32_dpp v137, v49, v167 row_shl:14 row_mask:0xf bank_mask:0xf
	v_fmac_f32_dpp v138, v50, v168 row_shl:14 row_mask:0xf bank_mask:0xf
	v_fmac_f32_dpp v139, v51, v169 row_shl:14 row_mask:0xf bank_mask:0xf
	v_pk_mul_f32 v[140:141], v[132:133], v[132:133]
	v_pk_mul_f32 v[142:143], v[134:135], v[134:135]
	v_pk_fma_f32 v[140:141], v[140:141], s[98:99], v[244:245]
	v_pk_fma_f32 v[142:143], v[142:143], s[98:99], v[244:245]
	v_pk_mul_f32 v[140:141], v[132:133], v[140:141]
	v_pk_mul_f32 v[142:143], v[134:135], v[142:143]
	v_exp_f32_e32 v140, v140
	v_exp_f32_e32 v141, v141
	v_exp_f32_e32 v142, v142
	v_exp_f32_e32 v143, v143
	v_pk_add_f32 v[140:141], v[140:141], s[100:101]
	v_pk_add_f32 v[142:143], v[142:143], s[100:101]
	v_rcp_f32_e32 v140, v140
	v_rcp_f32_e32 v141, v141
	v_rcp_f32_e32 v142, v142
	v_rcp_f32_e32 v143, v143
	v_pk_mul_f32 v[140:141], v[132:133], v[140:141]
	v_pk_mul_f32 v[142:143], v[134:135], v[142:143]
	v_pk_mul_f32 v[140:141], v[140:141], v[136:137]
	v_pk_mul_f32 v[142:143], v[142:143], v[138:139]
	v_cvt_pk_bf16_f32 v250, v140, v141
	v_cvt_pk_bf16_f32 v251, v142, v143
	v_pk_fma_f32 v[132:133], v[44:45], v[190:191], v[178:179]
	v_pk_fma_f32 v[136:137], v[24:25], v[206:207], v[194:195]
	v_pk_fma_f32 v[134:135], v[46:47], v[192:193], v[180:181]
	v_pk_fma_f32 v[138:139], v[26:27], v[208:209], v[196:197]
	v_fmac_f32_dpp v132, v44, v186 row_shr:1 row_mask:0xf bank_mask:0xf
	v_fmac_f32_dpp v133, v45, v187 row_shr:1 row_mask:0xf bank_mask:0xf
	v_fmac_f32_dpp v134, v46, v188 row_shr:1 row_mask:0xf bank_mask:0xf
	v_fmac_f32_dpp v135, v47, v189 row_shr:1 row_mask:0xf bank_mask:0xf
	v_fmac_f32_dpp v136, v24, v202 row_shr:1 row_mask:0xf bank_mask:0xf
	v_fmac_f32_dpp v137, v25, v203 row_shr:1 row_mask:0xf bank_mask:0xf
	v_fmac_f32_dpp v138, v26, v204 row_shr:1 row_mask:0xf bank_mask:0xf
	v_fmac_f32_dpp v139, v27, v205 row_shr:1 row_mask:0xf bank_mask:0xf
	v_fmac_f32_dpp v132, v56, v186 row_shl:15 row_mask:0xf bank_mask:0xf
	v_fmac_f32_dpp v133, v57, v187 row_shl:15 row_mask:0xf bank_mask:0xf
	v_fmac_f32_dpp v134, v58, v188 row_shl:15 row_mask:0xf bank_mask:0xf
	v_fmac_f32_dpp v135, v59, v189 row_shl:15 row_mask:0xf bank_mask:0xf
	v_fmac_f32_dpp v136, v40, v202 row_shl:15 row_mask:0xf bank_mask:0xf
	v_fmac_f32_dpp v137, v41, v203 row_shl:15 row_mask:0xf bank_mask:0xf
	v_fmac_f32_dpp v138, v42, v204 row_shl:15 row_mask:0xf bank_mask:0xf
	v_fmac_f32_dpp v139, v43, v205 row_shl:15 row_mask:0xf bank_mask:0xf
	v_fmac_f32_dpp v132, v44, v182 row_shr:2 row_mask:0xf bank_mask:0xf
	v_fmac_f32_dpp v133, v45, v183 row_shr:2 row_mask:0xf bank_mask:0xf
	v_fmac_f32_dpp v134, v46, v184 row_shr:2 row_mask:0xf bank_mask:0xf
	v_fmac_f32_dpp v135, v47, v185 row_shr:2 row_mask:0xf bank_mask:0xf
	v_fmac_f32_dpp v136, v24, v198 row_shr:2 row_mask:0xf bank_mask:0xf
	v_fmac_f32_dpp v137, v25, v199 row_shr:2 row_mask:0xf bank_mask:0xf
	v_fmac_f32_dpp v138, v26, v200 row_shr:2 row_mask:0xf bank_mask:0xf
	v_fmac_f32_dpp v139, v27, v201 row_shr:2 row_mask:0xf bank_mask:0xf
	v_fmac_f32_dpp v132, v56, v182 row_shl:14 row_mask:0xf bank_mask:0xf
	v_fmac_f32_dpp v133, v57, v183 row_shl:14 row_mask:0xf bank_mask:0xf
	v_fmac_f32_dpp v134, v58, v184 row_shl:14 row_mask:0xf bank_mask:0xf
	v_fmac_f32_dpp v135, v59, v185 row_shl:14 row_mask:0xf bank_mask:0xf
	v_fmac_f32_dpp v136, v40, v198 row_shl:14 row_mask:0xf bank_mask:0xf
	v_fmac_f32_dpp v137, v41, v199 row_shl:14 row_mask:0xf bank_mask:0xf
	v_fmac_f32_dpp v138, v42, v200 row_shl:14 row_mask:0xf bank_mask:0xf
	v_fmac_f32_dpp v139, v43, v201 row_shl:14 row_mask:0xf bank_mask:0xf
; __device__ __forceinline__ unsigned pk2(float lo, float hi) { unsigned r; asm("v_cvt_pk_bf16_f32 %0, %1, %2" : "=v"(r) : "v"(lo), "v"(hi)); return r; }
;     __device__ __forceinline__ void operator()(const f32x4 (&acc)[2][2][4][2], const Unit& u, int wr, int wc, int fr, int fq) const {
;     ...
; #pragma unroll
;             for (int ai = 0; ai < 2; ++ai)
; #pragma unroll
;                 for (int m = 0; m < 4; ++m) { const int row = row0 + ai * HALF + m * 16;
;                     const f32x4 g0 = acc[ai][0][m][n], v0 = acc[ai][1][m][n];
;                     f32x4 gp = (f32x4){0.f, 0.f, 0.f, 0.f}, vp = gp;
;                     if (m > 0) { gp = acc[ai][0][m > 0 ? m - 1 : 0][n]; vp = acc[ai][1][m > 0 ? m - 1 : 0][n]; }
;                     f32x4 f;
; #pragma unroll
;                     for (int j = 0; j < 4; ++j) {
;                         const float g1 = dpp_shr1(dpp_ror1(gp[j]), g0[j]), g2 = dpp_shr2(dpp_ror2(gp[j]), g0[j]);
;                         const float v1 = dpp_shr1(dpp_ror1(vp[j]), v0[j]), v2 = dpp_shr2(dpp_ror2(vp[j]), v0[j]);
;                         const float cg_ = bg[j] + g2 * wg0[j] + g1 * wg1[j] + g0[j] * wg2[j];
;                         const float cv_ = bv[j] + v2 * wv0[j] + v1 * wv1[j] + v0[j] * wv2[j];
;                         f[j] = gelu_tanh(cg_) * cv_; }
;                     u32x2 w; w.x = pk2(f[0], f[1]); w.y = pk2(f[2], f[3]);
;                     if (n == 0) res0[ai * 4 + m] = w;
;                     else if (m > 0 || fr >= 2) { u32x4 w4; w4.x = res0[ai * 4 + m].x; w4.y = res0[ai * 4 + m].y; w4.z = w.x; w4.w = w.y; *(u32x4*)(F + (size_t)row * DFF + j0) = w4; }
;                     if (n == 1 && ((m == 0 && fr < 2) || (m == 3 && fr >= 14))) { const int slot = m == 0 ? fr : fr - 12;
;                         const f32x4 ga = acc[ai][0][m][0], va = acc[ai][1][m][0];
;                         bf16_t* bp = UPB + ((size_t)(row >> 6) * 4 + slot) * (2 * DFF) + col0;
;                         u32x4 wg_, wv_; wg_.x = pk2(ga[0], ga[1]); wg_.y = pk2(ga[2], ga[3]); wg_.z = pk2(g0[0], g0[1]); wg_.w = pk2(g0[2], g0[3]);
;                         wv_.x = pk2(va[0], va[1]); wv_.y = pk2(va[2], va[3]); wv_.z = pk2(v0[0], v0[1]); wv_.w = pk2(v0[2], v0[3]);
;                         *(u32x4*)bp = wg_; *(u32x4*)(bp + HALF) = wv_; } }
	v_pk_mul_f32 v[140:141], v[132:133], v[132:133]
	v_pk_mul_f32 v[142:143], v[134:135], v[134:135]
	v_pk_fma_f32 v[140:141], v[140:141], s[98:99], v[244:245]
	v_pk_fma_f32 v[142:143], v[142:143], s[98:99], v[244:245]
	v_pk_mul_f32 v[140:141], v[132:133], v[140:141]
	v_pk_mul_f32 v[142:143], v[134:135], v[142:143]
	v_exp_f32_e32 v140, v140
	v_exp_f32_e32 v141, v141
	v_exp_f32_e32 v142, v142
	v_exp_f32_e32 v143, v143
	v_pk_add_f32 v[140:141], v[140:141], s[100:101]
	v_pk_add_f32 v[142:143], v[142:143], s[100:101]
	v_rcp_f32_e32 v140, v140
	v_rcp_f32_e32 v141, v141
	v_rcp_f32_e32 v142, v142
	v_rcp_f32_e32 v143, v143
	v_pk_mul_f32 v[140:141], v[132:133], v[140:141]
	v_pk_mul_f32 v[142:143], v[134:135], v[142:143]
	v_pk_mul_f32 v[140:141], v[140:141], v[136:137]
	v_pk_mul_f32 v[142:143], v[142:143], v[138:139]
	v_cvt_pk_bf16_f32 v252, v140, v141
	v_cvt_pk_bf16_f32 v253, v142, v143
	v_add_u32_e32 v144, 0x90, v248
	v_mad_u64_u32 v[144:145], vcc, v144, s4, v[242:243]
	global_store_dwordx4 v[144:145], v[250:253], off nt
	v_pk_fma_f32 v[132:133], v[36:37], v[158:159], v[146:147]
	v_pk_fma_f32 v[136:137], v[16:17], v[174:175], v[162:163]
	v_pk_fma_f32 v[134:135], v[38:39], v[160:161], v[148:149]
	v_pk_fma_f32 v[138:139], v[18:19], v[176:177], v[164:165]
	v_fmac_f32_dpp v132, v36, v154 row_shr:1 row_mask:0xf bank_mask:0xf
	v_fmac_f32_dpp v133, v37, v155 row_shr:1 row_mask:0xf bank_mask:0xf
	v_fmac_f32_dpp v134, v38, v156 row_shr:1 row_mask:0xf bank_mask:0xf
	v_fmac_f32_dpp v135, v39, v157 row_shr:1 row_mask:0xf bank_mask:0xf
	v_fmac_f32_dpp v136, v16, v170 row_shr:1 row_mask:0xf bank_mask:0xf
	v_fmac_f32_dpp v137, v17, v171 row_shr:1 row_mask:0xf bank_mask:0xf
	v_fmac_f32_dpp v138, v18, v172 row_shr:1 row_mask:0xf bank_mask:0xf
	v_fmac_f32_dpp v139, v19, v173 row_shr:1 row_mask:0xf bank_mask:0xf
	v_fmac_f32_dpp v132, v52, v154 row_shl:15 row_mask:0xf bank_mask:0xf
	v_fmac_f32_dpp v133, v53, v155 row_shl:15 row_mask:0xf bank_mask:0xf
	v_fmac_f32_dpp v134, v54, v156 row_shl:15 row_mask:0xf bank_mask:0xf
	v_fmac_f32_dpp v135, v55, v157 row_shl:15 row_mask:0xf bank_mask:0xf
	v_fmac_f32_dpp v136, v32, v170 row_shl:15 row_mask:0xf bank_mask:0xf
	v_fmac_f32_dpp v137, v33, v171 row_shl:15 row_mask:0xf bank_mask:0xf
	v_fmac_f32_dpp v138, v34, v172 row_shl:15 row_mask:0xf bank_mask:0xf
	v_fmac_f32_dpp v139, v35, v173 row_shl:15 row_mask:0xf bank_mask:0xf
	v_fmac_f32_dpp v132, v36, v150 row_shr:2 row_mask:0xf bank_mask:0xf
	v_fmac_f32_dpp v133, v37, v151 row_shr:2 row_mask:0xf bank_mask:0xf
	v_fmac_f32_dpp v134, v38, v152 row_shr:2 row_mask:0xf bank_mask:0xf
	v_fmac_f32_dpp v135, v39, v153 row_shr:2 row_mask:0xf bank_mask:0xf
	v_fmac_f32_dpp v136, v16, v166 row_shr:2 row_mask:0xf bank_mask:0xf
	v_fmac_f32_dpp v137, v17, v167 row_shr:2 row_mask:0xf bank_mask:0xf
	v_fmac_f32_dpp v138, v18, v168 row_shr:2 row_mask:0xf bank_mask:0xf
	v_fmac_f32_dpp v139, v19, v169 row_shr:2 row_mask:0xf bank_mask:0xf
	v_fmac_f32_dpp v132, v52, v150 row_shl:14 row_mask:0xf bank_mask:0xf
	v_fmac_f32_dpp v133, v53, v151 row_shl:14 row_mask:0xf bank_mask:0xf
	v_fmac_f32_dpp v134, v54, v152 row_shl:14 row_mask:0xf bank_mask:0xf
	v_fmac_f32_dpp v135, v55, v153 row_shl:14 row_mask:0xf bank_mask:0xf
	v_fmac_f32_dpp v136, v32, v166 row_shl:14 row_mask:0xf bank_mask:0xf
	v_fmac_f32_dpp v137, v33, v167 row_shl:14 row_mask:0xf bank_mask:0xf
	v_fmac_f32_dpp v138, v34, v168 row_shl:14 row_mask:0xf bank_mask:0xf
	v_fmac_f32_dpp v139, v35, v169 row_shl:14 row_mask:0xf bank_mask:0xf
	v_pk_mul_f32 v[140:141], v[132:133], v[132:133]
	v_pk_mul_f32 v[142:143], v[134:135], v[134:135]
	v_pk_fma_f32 v[140:141], v[140:141], s[98:99], v[244:245]
	v_pk_fma_f32 v[142:143], v[142:143], s[98:99], v[244:245]
	v_pk_mul_f32 v[140:141], v[132:133], v[140:141]
	v_pk_mul_f32 v[142:143], v[134:135], v[142:143]
	v_exp_f32_e32 v140, v140
	v_exp_f32_e32 v141, v141
	v_exp_f32_e32 v142, v142
	v_exp_f32_e32 v143, v143
	v_pk_add_f32 v[140:141], v[140:141], s[100:101]
	v_pk_add_f32 v[142:143], v[142:143], s[100:101]
	v_rcp_f32_e32 v140, v140
	v_rcp_f32_e32 v141, v141
	v_rcp_f32_e32 v142, v142
	v_rcp_f32_e32 v143, v143
	v_pk_mul_f32 v[140:141], v[132:133], v[140:141]
	v_pk_mul_f32 v[142:143], v[134:135], v[142:143]
	v_pk_mul_f32 v[140:141], v[140:141], v[136:137]
	v_pk_mul_f32 v[142:143], v[142:143], v[138:139]
	v_cvt_pk_bf16_f32 v128, v140, v141
	v_cvt_pk_bf16_f32 v129, v142, v143
	v_pk_fma_f32 v[132:133], v[28:29], v[190:191], v[178:179]
	v_pk_fma_f32 v[136:137], v[8:9], v[206:207], v[194:195]
	v_pk_fma_f32 v[134:135], v[30:31], v[192:193], v[180:181]
	v_pk_fma_f32 v[138:139], v[10:11], v[208:209], v[196:197]
	v_fmac_f32_dpp v132, v28, v186 row_shr:1 row_mask:0xf bank_mask:0xf
	v_fmac_f32_dpp v133, v29, v187 row_shr:1 row_mask:0xf bank_mask:0xf
	v_fmac_f32_dpp v134, v30, v188 row_shr:1 row_mask:0xf bank_mask:0xf
	v_fmac_f32_dpp v135, v31, v189 row_shr:1 row_mask:0xf bank_mask:0xf
	v_fmac_f32_dpp v136, v8, v202 row_shr:1 row_mask:0xf bank_mask:0xf
	v_fmac_f32_dpp v137, v9, v203 row_shr:1 row_mask:0xf bank_mask:0xf
	v_fmac_f32_dpp v138, v10, v204 row_shr:1 row_mask:0xf bank_mask:0xf
	v_fmac_f32_dpp v139, v11, v205 row_shr:1 row_mask:0xf bank_mask:0xf
	v_fmac_f32_dpp v132, v44, v186 row_shl:15 row_mask:0xf bank_mask:0xf
	v_fmac_f32_dpp v133, v45, v187 row_shl:15 row_mask:0xf bank_mask:0xf
	v_fmac_f32_dpp v134, v46, v188 row_shl:15 row_mask:0xf bank_mask:0xf
	v_fmac_f32_dpp v135, v47, v189 row_shl:15 row_mask:0xf bank_mask:0xf
	v_fmac_f32_dpp v136, v24, v202 row_shl:15 row_mask:0xf bank_mask:0xf
	v_fmac_f32_dpp v137, v25, v203 row_shl:15 row_mask:0xf bank_mask:0xf
	v_fmac_f32_dpp v138, v26, v204 row_shl:15 row_mask:0xf bank_mask:0xf
; __device__ __forceinline__ unsigned pk2(float lo, float hi) { unsigned r; asm("v_cvt_pk_bf16_f32 %0, %1, %2" : "=v"(r) : "v"(lo), "v"(hi)); return r; }
;     __device__ __forceinline__ void operator()(const f32x4 (&acc)[2][2][4][2], const Unit& u, int wr, int wc, int fr, int fq) const {
;     ...
; #pragma unroll
;             for (int ai = 0; ai < 2; ++ai)
; #pragma unroll
;                 for (int m = 0; m < 4; ++m) { const int row = row0 + ai * HALF + m * 16;
;                     const f32x4 g0 = acc[ai][0][m][n], v0 = acc[ai][1][m][n];
;                     f32x4 gp = (f32x4){0.f, 0.f, 0.f, 0.f}, vp = gp;
;                     if (m > 0) { gp = acc[ai][0][m > 0 ? m - 1 : 0][n]; vp = acc[ai][1][m > 0 ? m - 1 : 0][n]; }
;                     f32x4 f;
; #pragma unroll
;                     for (int j = 0; j < 4; ++j) {
;                         const float g1 = dpp_shr1(dpp_ror1(gp[j]), g0[j]), g2 = dpp_shr2(dpp_ror2(gp[j]), g0[j]);
;                         const float v1 = dpp_shr1(dpp_ror1(vp[j]), v0[j]), v2 = dpp_shr2(dpp_ror2(vp[j]), v0[j]);
;                         const float cg_ = bg[j] + g2 * wg0[j] + g1 * wg1[j] + g0[j] * wg2[j];
;                         const float cv_ = bv[j] + v2 * wv0[j] + v1 * wv1[j] + v0[j] * wv2[j];
;                         f[j] = gelu_tanh(cg_) * cv_; }
;                     u32x2 w; w.x = pk2(f[0], f[1]); w.y = pk2(f[2], f[3]);
;                     if (n == 0) res0[ai * 4 + m] = w;
;                     else if (m > 0 || fr >= 2) { u32x4 w4; w4.x = res0[ai * 4 + m].x; w4.y = res0[ai * 4 + m].y; w4.z = w.x; w4.w = w.y; *(u32x4*)(F + (size_t)row * DFF + j0) = w4; }
;                     if (n == 1 && ((m == 0 && fr < 2) || (m == 3 && fr >= 14))) { const int slot = m == 0 ? fr : fr - 12;
;                         const f32x4 ga = acc[ai][0][m][0], va = acc[ai][1][m][0];
;                         bf16_t* bp = UPB + ((size_t)(row >> 6) * 4 + slot) * (2 * DFF) + col0;
;                         u32x4 wg_, wv_; wg_.x = pk2(ga[0], ga[1]); wg_.y = pk2(ga[2], ga[3]); wg_.z = pk2(g0[0], g0[1]); wg_.w = pk2(g0[2], g0[3]);
;                         wv_.x = pk2(va[0], va[1]); wv_.y = pk2(va[2], va[3]); wv_.z = pk2(v0[0], v0[1]); wv_.w = pk2(v0[2], v0[3]);
;                         *(u32x4*)bp = wg_; *(u32x4*)(bp + HALF) = wv_; } }
	v_fmac_f32_dpp v139, v27, v205 row_shl:15 row_mask:0xf bank_mask:0xf
	v_fmac_f32_dpp v132, v28, v182 row_shr:2 row_mask:0xf bank_mask:0xf
	v_fmac_f32_dpp v133, v29, v183 row_shr:2 row_mask:0xf bank_mask:0xf
	v_fmac_f32_dpp v134, v30, v184 row_shr:2 row_mask:0xf bank_mask:0xf
	v_fmac_f32_dpp v135, v31, v185 row_shr:2 row_mask:0xf bank_mask:0xf
	v_fmac_f32_dpp v136, v8, v198 row_shr:2 row_mask:0xf bank_mask:0xf
	v_fmac_f32_dpp v137, v9, v199 row_shr:2 row_mask:0xf bank_mask:0xf
	v_fmac_f32_dpp v138, v10, v200 row_shr:2 row_mask:0xf bank_mask:0xf
	v_fmac_f32_dpp v139, v11, v201 row_shr:2 row_mask:0xf bank_mask:0xf
	v_fmac_f32_dpp v132, v44, v182 row_shl:14 row_mask:0xf bank_mask:0xf
	v_fmac_f32_dpp v133, v45, v183 row_shl:14 row_mask:0xf bank_mask:0xf
	v_fmac_f32_dpp v134, v46, v184 row_shl:14 row_mask:0xf bank_mask:0xf
	v_fmac_f32_dpp v135, v47, v185 row_shl:14 row_mask:0xf bank_mask:0xf
	v_fmac_f32_dpp v136, v24, v198 row_shl:14 row_mask:0xf bank_mask:0xf
	v_fmac_f32_dpp v137, v25, v199 row_shl:14 row_mask:0xf bank_mask:0xf
	v_fmac_f32_dpp v138, v26, v200 row_shl:14 row_mask:0xf bank_mask:0xf
	v_fmac_f32_dpp v139, v27, v201 row_shl:14 row_mask:0xf bank_mask:0xf
	v_pk_mul_f32 v[140:141], v[132:133], v[132:133]
	v_pk_mul_f32 v[142:143], v[134:135], v[134:135]
	v_pk_fma_f32 v[140:141], v[140:141], s[98:99], v[244:245]
	v_pk_fma_f32 v[142:143], v[142:143], s[98:99], v[244:245]
	v_pk_mul_f32 v[140:141], v[132:133], v[140:141]
	v_pk_mul_f32 v[142:143], v[134:135], v[142:143]
	v_exp_f32_e32 v140, v140
	v_exp_f32_e32 v141, v141
	v_exp_f32_e32 v142, v142
	v_exp_f32_e32 v143, v143
	v_pk_add_f32 v[140:141], v[140:141], s[100:101]
	v_pk_add_f32 v[142:143], v[142:143], s[100:101]
	v_rcp_f32_e32 v140, v140
	v_rcp_f32_e32 v141, v141
	v_rcp_f32_e32 v142, v142
	v_rcp_f32_e32 v143, v143
	v_pk_mul_f32 v[140:141], v[132:133], v[140:141]
	v_pk_mul_f32 v[142:143], v[134:135], v[142:143]
	v_pk_mul_f32 v[140:141], v[140:141], v[136:137]
	v_pk_mul_f32 v[142:143], v[142:143], v[138:139]
	v_cvt_pk_bf16_f32 v130, v140, v141
	v_cvt_pk_bf16_f32 v131, v142, v143
	v_add_u32_e32 v144, 0xa0, v248
	v_mad_u64_u32 v[144:145], vcc, v144, s4, v[242:243]
	global_store_dwordx4 v[144:145], v[128:131], off nt
	v_pk_fma_f32 v[132:133], v[20:21], v[158:159], v[146:147]
	v_pk_fma_f32 v[136:137], v[4:5], v[174:175], v[162:163]
	v_pk_fma_f32 v[134:135], v[22:23], v[160:161], v[148:149]
	v_pk_fma_f32 v[138:139], v[6:7], v[176:177], v[164:165]
	v_fmac_f32_dpp v132, v20, v154 row_shr:1 row_mask:0xf bank_mask:0xf
	v_fmac_f32_dpp v133, v21, v155 row_shr:1 row_mask:0xf bank_mask:0xf
	v_fmac_f32_dpp v134, v22, v156 row_shr:1 row_mask:0xf bank_mask:0xf
	v_fmac_f32_dpp v135, v23, v157 row_shr:1 row_mask:0xf bank_mask:0xf
	v_fmac_f32_dpp v136, v4, v170 row_shr:1 row_mask:0xf bank_mask:0xf
	v_fmac_f32_dpp v137, v5, v171 row_shr:1 row_mask:0xf bank_mask:0xf
	v_fmac_f32_dpp v138, v6, v172 row_shr:1 row_mask:0xf bank_mask:0xf
	v_fmac_f32_dpp v139, v7, v173 row_shr:1 row_mask:0xf bank_mask:0xf
	v_fmac_f32_dpp v132, v36, v154 row_shl:15 row_mask:0xf bank_mask:0xf
	v_fmac_f32_dpp v133, v37, v155 row_shl:15 row_mask:0xf bank_mask:0xf
	v_fmac_f32_dpp v134, v38, v156 row_shl:15 row_mask:0xf bank_mask:0xf
	v_fmac_f32_dpp v135, v39, v157 row_shl:15 row_mask:0xf bank_mask:0xf
	v_fmac_f32_dpp v136, v16, v170 row_shl:15 row_mask:0xf bank_mask:0xf
	v_fmac_f32_dpp v137, v17, v171 row_shl:15 row_mask:0xf bank_mask:0xf
	v_fmac_f32_dpp v138, v18, v172 row_shl:15 row_mask:0xf bank_mask:0xf
	v_fmac_f32_dpp v139, v19, v173 row_shl:15 row_mask:0xf bank_mask:0xf
	v_fmac_f32_dpp v132, v20, v150 row_shr:2 row_mask:0xf bank_mask:0xf
	v_fmac_f32_dpp v133, v21, v151 row_shr:2 row_mask:0xf bank_mask:0xf
	v_fmac_f32_dpp v134, v22, v152 row_shr:2 row_mask:0xf bank_mask:0xf
	v_fmac_f32_dpp v135, v23, v153 row_shr:2 row_mask:0xf bank_mask:0xf
	v_fmac_f32_dpp v136, v4, v166 row_shr:2 row_mask:0xf bank_mask:0xf
	v_fmac_f32_dpp v137, v5, v167 row_shr:2 row_mask:0xf bank_mask:0xf
	v_fmac_f32_dpp v138, v6, v168 row_shr:2 row_mask:0xf bank_mask:0xf
	v_fmac_f32_dpp v139, v7, v169 row_shr:2 row_mask:0xf bank_mask:0xf
	v_fmac_f32_dpp v132, v36, v150 row_shl:14 row_mask:0xf bank_mask:0xf
	v_fmac_f32_dpp v133, v37, v151 row_shl:14 row_mask:0xf bank_mask:0xf
	v_fmac_f32_dpp v134, v38, v152 row_shl:14 row_mask:0xf bank_mask:0xf
	v_fmac_f32_dpp v135, v39, v153 row_shl:14 row_mask:0xf bank_mask:0xf
	v_fmac_f32_dpp v136, v16, v166 row_shl:14 row_mask:0xf bank_mask:0xf
	v_fmac_f32_dpp v137, v17, v167 row_shl:14 row_mask:0xf bank_mask:0xf
	v_fmac_f32_dpp v138, v18, v168 row_shl:14 row_mask:0xf bank_mask:0xf
	v_fmac_f32_dpp v139, v19, v169 row_shl:14 row_mask:0xf bank_mask:0xf
	v_pk_mul_f32 v[140:141], v[132:133], v[132:133]
	v_pk_mul_f32 v[142:143], v[134:135], v[134:135]
	v_pk_fma_f32 v[140:141], v[140:141], s[98:99], v[244:245]
; __device__ __forceinline__ unsigned pk2(float lo, float hi) { unsigned r; asm("v_cvt_pk_bf16_f32 %0, %1, %2" : "=v"(r) : "v"(lo), "v"(hi)); return r; }
;     __device__ __forceinline__ void operator()(const f32x4 (&acc)[2][2][4][2], const Unit& u, int wr, int wc, int fr, int fq) const {
;     ...
; #pragma unroll
;             for (int ai = 0; ai < 2; ++ai)
; #pragma unroll
;                 for (int m = 0; m < 4; ++m) { const int row = row0 + ai * HALF + m * 16;
;                     const f32x4 g0 = acc[ai][0][m][n], v0 = acc[ai][1][m][n];
;                     f32x4 gp = (f32x4){0.f, 0.f, 0.f, 0.f}, vp = gp;
;                     if (m > 0) { gp = acc[ai][0][m > 0 ? m - 1 : 0][n]; vp = acc[ai][1][m > 0 ? m - 1 : 0][n]; }
;                     f32x4 f;
; #pragma unroll
;                     for (int j = 0; j < 4; ++j) {
;                         const float g1 = dpp_shr1(dpp_ror1(gp[j]), g0[j]), g2 = dpp_shr2(dpp_ror2(gp[j]), g0[j]);
;                         const float v1 = dpp_shr1(dpp_ror1(vp[j]), v0[j]), v2 = dpp_shr2(dpp_ror2(vp[j]), v0[j]);
;                         const float cg_ = bg[j] + g2 * wg0[j] + g1 * wg1[j] + g0[j] * wg2[j];
;                         const float cv_ = bv[j] + v2 * wv0[j] + v1 * wv1[j] + v0[j] * wv2[j];
;                         f[j] = gelu_tanh(cg_) * cv_; }
;                     u32x2 w; w.x = pk2(f[0], f[1]); w.y = pk2(f[2], f[3]);
;                     if (n == 0) res0[ai * 4 + m] = w;
;                     else if (m > 0 || fr >= 2) { u32x4 w4; w4.x = res0[ai * 4 + m].x; w4.y = res0[ai * 4 + m].y; w4.z = w.x; w4.w = w.y; *(u32x4*)(F + (size_t)row * DFF + j0) = w4; }
;                     if (n == 1 && ((m == 0 && fr < 2) || (m == 3 && fr >= 14))) { const int slot = m == 0 ? fr : fr - 12;
;                         const f32x4 ga = acc[ai][0][m][0], va = acc[ai][1][m][0];
;                         bf16_t* bp = UPB + ((size_t)(row >> 6) * 4 + slot) * (2 * DFF) + col0;
;                         u32x4 wg_, wv_; wg_.x = pk2(ga[0], ga[1]); wg_.y = pk2(ga[2], ga[3]); wg_.z = pk2(g0[0], g0[1]); wg_.w = pk2(g0[2], g0[3]);
;                         wv_.x = pk2(va[0], va[1]); wv_.y = pk2(va[2], va[3]); wv_.z = pk2(v0[0], v0[1]); wv_.w = pk2(v0[2], v0[3]);
;                         *(u32x4*)bp = wg_; *(u32x4*)(bp + HALF) = wv_; } }
	v_pk_fma_f32 v[142:143], v[142:143], s[98:99], v[244:245]
	v_pk_mul_f32 v[140:141], v[132:133], v[140:141]
	v_pk_mul_f32 v[142:143], v[134:135], v[142:143]
	v_exp_f32_e32 v140, v140
	v_exp_f32_e32 v141, v141
	v_exp_f32_e32 v142, v142
	v_exp_f32_e32 v143, v143
	v_pk_add_f32 v[140:141], v[140:141], s[100:101]
	v_pk_add_f32 v[142:143], v[142:143], s[100:101]
	v_rcp_f32_e32 v140, v140
	v_rcp_f32_e32 v141, v141
	v_rcp_f32_e32 v142, v142
	v_rcp_f32_e32 v143, v143
	v_pk_mul_f32 v[140:141], v[132:133], v[140:141]
	v_pk_mul_f32 v[142:143], v[134:135], v[142:143]
	v_pk_mul_f32 v[140:141], v[140:141], v[136:137]
	v_pk_mul_f32 v[142:143], v[142:143], v[138:139]
	v_cvt_pk_bf16_f32 v250, v140, v141
	v_cvt_pk_bf16_f32 v251, v142, v143
	v_pk_fma_f32 v[132:133], v[12:13], v[190:191], v[178:179]
	v_pk_fma_f32 v[136:137], v[0:1], v[206:207], v[194:195]
	v_pk_fma_f32 v[134:135], v[14:15], v[192:193], v[180:181]
	v_pk_fma_f32 v[138:139], v[2:3], v[208:209], v[196:197]
	v_fmac_f32_dpp v132, v12, v186 row_shr:1 row_mask:0xf bank_mask:0xf
	v_fmac_f32_dpp v133, v13, v187 row_shr:1 row_mask:0xf bank_mask:0xf
	v_fmac_f32_dpp v134, v14, v188 row_shr:1 row_mask:0xf bank_mask:0xf
	v_fmac_f32_dpp v135, v15, v189 row_shr:1 row_mask:0xf bank_mask:0xf
	v_fmac_f32_dpp v136, v0, v202 row_shr:1 row_mask:0xf bank_mask:0xf
	v_fmac_f32_dpp v137, v1, v203 row_shr:1 row_mask:0xf bank_mask:0xf
	v_fmac_f32_dpp v138, v2, v204 row_shr:1 row_mask:0xf bank_mask:0xf
	v_fmac_f32_dpp v139, v3, v205 row_shr:1 row_mask:0xf bank_mask:0xf
	v_fmac_f32_dpp v132, v28, v186 row_shl:15 row_mask:0xf bank_mask:0xf
	v_fmac_f32_dpp v133, v29, v187 row_shl:15 row_mask:0xf bank_mask:0xf
	v_fmac_f32_dpp v134, v30, v188 row_shl:15 row_mask:0xf bank_mask:0xf
	v_fmac_f32_dpp v135, v31, v189 row_shl:15 row_mask:0xf bank_mask:0xf
	v_fmac_f32_dpp v136, v8, v202 row_shl:15 row_mask:0xf bank_mask:0xf
	v_fmac_f32_dpp v137, v9, v203 row_shl:15 row_mask:0xf bank_mask:0xf
	v_fmac_f32_dpp v138, v10, v204 row_shl:15 row_mask:0xf bank_mask:0xf
	v_fmac_f32_dpp v139, v11, v205 row_shl:15 row_mask:0xf bank_mask:0xf
	v_fmac_f32_dpp v132, v12, v182 row_shr:2 row_mask:0xf bank_mask:0xf
	v_fmac_f32_dpp v133, v13, v183 row_shr:2 row_mask:0xf bank_mask:0xf
	v_fmac_f32_dpp v134, v14, v184 row_shr:2 row_mask:0xf bank_mask:0xf
	v_fmac_f32_dpp v135, v15, v185 row_shr:2 row_mask:0xf bank_mask:0xf
	v_fmac_f32_dpp v136, v0, v198 row_shr:2 row_mask:0xf bank_mask:0xf
	v_fmac_f32_dpp v137, v1, v199 row_shr:2 row_mask:0xf bank_mask:0xf
	v_fmac_f32_dpp v138, v2, v200 row_shr:2 row_mask:0xf bank_mask:0xf
	v_fmac_f32_dpp v139, v3, v201 row_shr:2 row_mask:0xf bank_mask:0xf
	v_fmac_f32_dpp v132, v28, v182 row_shl:14 row_mask:0xf bank_mask:0xf
	v_fmac_f32_dpp v133, v29, v183 row_shl:14 row_mask:0xf bank_mask:0xf
	v_fmac_f32_dpp v134, v30, v184 row_shl:14 row_mask:0xf bank_mask:0xf
	v_fmac_f32_dpp v135, v31, v185 row_shl:14 row_mask:0xf bank_mask:0xf
	v_fmac_f32_dpp v136, v8, v198 row_shl:14 row_mask:0xf bank_mask:0xf
	v_fmac_f32_dpp v137, v9, v199 row_shl:14 row_mask:0xf bank_mask:0xf
	v_fmac_f32_dpp v138, v10, v200 row_shl:14 row_mask:0xf bank_mask:0xf
	v_fmac_f32_dpp v139, v11, v201 row_shl:14 row_mask:0xf bank_mask:0xf
	v_pk_mul_f32 v[140:141], v[132:133], v[132:133]
	v_pk_mul_f32 v[142:143], v[134:135], v[134:135]
	v_pk_fma_f32 v[140:141], v[140:141], s[98:99], v[244:245]
	v_pk_fma_f32 v[142:143], v[142:143], s[98:99], v[244:245]
	v_pk_mul_f32 v[140:141], v[132:133], v[140:141]
	v_pk_mul_f32 v[142:143], v[134:135], v[142:143]
	v_exp_f32_e32 v140, v140
	v_exp_f32_e32 v141, v141
	v_exp_f32_e32 v142, v142
	v_exp_f32_e32 v143, v143
	v_pk_add_f32 v[140:141], v[140:141], s[100:101]
	v_pk_add_f32 v[142:143], v[142:143], s[100:101]
	v_rcp_f32_e32 v140, v140
	v_rcp_f32_e32 v141, v141
	v_rcp_f32_e32 v142, v142
	v_rcp_f32_e32 v143, v143
	v_pk_mul_f32 v[140:141], v[132:133], v[140:141]
	v_pk_mul_f32 v[142:143], v[134:135], v[142:143]
	v_pk_mul_f32 v[140:141], v[140:141], v[136:137]
	v_pk_mul_f32 v[142:143], v[142:143], v[138:139]
	v_cvt_pk_bf16_f32 v252, v140, v141
	v_cvt_pk_bf16_f32 v253, v142, v143
	v_add_u32_e32 v144, 0xb0, v248
	v_mad_u64_u32 v[144:145], vcc, v144, s4, v[242:243]
	global_store_dwordx4 v[144:145], v[250:253], off nt
	s_mov_b64 s[0:1], 0
	s_and_saveexec_b64 s[42:43], s[12:13]
	s_xor_b64 s[52:53], exec, s[42:43]
	s_cbranch_execz .LBB0_1214
	v_add_u32_e32 v144, s73, v234
	v_mov_b64_e32 v[132:133], s[80:81]
	v_mad_u64_u32 v[132:133], vcc, v144, s83, v[132:133]
	v_lshl_add_u64 v[132:133], v[240:241], 1, v[132:133]
	s_mov_b64 s[72:73], exec
	v_cvt_pk_bf16_f32 v134, v20, v21
	v_cvt_pk_bf16_f32 v135, v22, v23
	v_cvt_pk_bf16_f32 v136, v12, v13
	v_cvt_pk_bf16_f32 v137, v14, v15
	v_cvt_pk_bf16_f32 v128, v4, v5
	v_cvt_pk_bf16_f32 v129, v6, v7
	v_cvt_pk_bf16_f32 v130, v0, v1
	v_cvt_pk_bf16_f32 v131, v2, v3
	global_store_dwordx4 v[132:133], v[134:137], off

; #define LAS __attribute__((address_space(3)))
; __global__ void __launch_bounds__(NTHREADS, 2) fwd_megakernel(Params p) {
;     extern __shared__ __attribute__((aligned(16))) unsigned char lds_raw[];
;     LAS unsigned char* lds = (LAS unsigned char*)lds_raw;
	.amdhsa_kernel _Z14fwd_megakernel6Params
		.amdhsa_group_segment_fixed_size 8192
		.amdhsa_private_segment_fixed_size 0
		.amdhsa_kernarg_size 520
		.amdhsa_user_sgpr_count 2
		.amdhsa_user_sgpr_dispatch_ptr 0
		.amdhsa_user_sgpr_queue_ptr 0
		.amdhsa_user_sgpr_kernarg_segment_ptr 1
		.amdhsa_user_sgpr_dispatch_id 0
		.amdhsa_user_sgpr_kernarg_preload_length 0
		.amdhsa_user_sgpr_kernarg_preload_offset 0
		.amdhsa_user_sgpr_private_segment_size 0
		.amdhsa_uses_dynamic_stack 0
		.amdhsa_enable_private_segment 0
		.amdhsa_system_sgpr_workgroup_id_x 1
		.amdhsa_system_sgpr_workgroup_id_y 0
		.amdhsa_system_sgpr_workgroup_id_z 0
		.amdhsa_system_sgpr_workgroup_info 0
		.amdhsa_system_vgpr_workitem_id 2
		.amdhsa_next_free_vgpr 256
		.amdhsa_next_free_sgpr 102
		.amdhsa_accum_offset 256
		.amdhsa_reserve_vcc 1
		.amdhsa_float_round_mode_32 0
		.amdhsa_float_round_mode_16_64 0
		.amdhsa_float_denorm_mode_32 3
		.amdhsa_float_denorm_mode_16_64 3
		.amdhsa_dx10_clamp 1
		.amdhsa_ieee_mode 1
		.amdhsa_fp16_overflow 0
		.amdhsa_tg_split 0
		.amdhsa_exception_fp_ieee_invalid_op 0
		.amdhsa_exception_fp_denorm_src 0
		.amdhsa_exception_fp_ieee_div_zero 0
		.amdhsa_exception_fp_ieee_overflow 0
		.amdhsa_exception_fp_ieee_underflow 0
		.amdhsa_exception_fp_ieee_inexact 0
		.amdhsa_exception_int_div_zero 0
	.end_amdhsa_kernel

; #define LAS __attribute__((address_space(3)))
; __global__ void __launch_bounds__(NTHREADS, 2) fwd_megakernel(Params p) {
;     extern __shared__ __attribute__((aligned(16))) unsigned char lds_raw[];
;     LAS unsigned char* lds = (LAS unsigned char*)lds_raw;
amdhsa.kernels:
  - .agpr_count:     0
    .args:
      - .offset:         0
        .size:           264
        .value_kind:     by_value
      - .offset:         264
        .size:           4
        .value_kind:     hidden_block_count_x
      - .offset:         268
        .size:           4
        .value_kind:     hidden_block_count_y
      - .offset:         272
        .size:           4
        .value_kind:     hidden_block_count_z
      - .offset:         276
        .size:           2
        .value_kind:     hidden_group_size_x
      - .offset:         278
        .size:           2
        .value_kind:     hidden_group_size_y
      - .offset:         280
        .size:           2
        .value_kind:     hidden_group_size_z
      - .offset:         282
        .size:           2
        .value_kind:     hidden_remainder_x
      - .offset:         284
        .size:           2
        .value_kind:     hidden_remainder_y
      - .offset:         286
        .size:           2
        .value_kind:     hidden_remainder_z
      - .offset:         304
        .size:           8
        .value_kind:     hidden_global_offset_x
      - .offset:         312
        .size:           8
        .value_kind:     hidden_global_offset_y
      - .offset:         320
        .size:           8
        .value_kind:     hidden_global_offset_z
      - .offset:         328
        .size:           2
        .value_kind:     hidden_grid_dims
      - .offset:         352
        .size:           8
        .value_kind:     hidden_multigrid_sync_arg
      - .offset:         384
        .size:           4
        .value_kind:     hidden_dynamic_lds_size
    .group_segment_fixed_size: 8192
    .kernarg_segment_align: 8
    .kernarg_segment_size: 520
    .language:       OpenCL C
    .language_version:
      - 2
      - 0
    .max_flat_workgroup_size: 512
    .name:           _Z14fwd_megakernel6Params
    .private_segment_fixed_size: 0
    .sgpr_count:     108
    .sgpr_spill_count: 87
    .symbol:         _Z14fwd_megakernel6Params.kd
    .uniform_work_group_size: 1
    .uses_dynamic_stack: false
    .vgpr_count:     256
    .vgpr_spill_count: 0
    .wavefront_size: 64
